# static priority offset for the younger wave half (waves 4..7) in the FFN-up K loop: that half runs a loop copy with s_setprio 2/1 instead of 1/0
# speedup vs baseline: 1.0577x; 1.0005x over previous
; template <class Epi, class S_t>
; __device__ __forceinline__ void gemm_phase(LAS unsigned char* lds, int lda, int ldb, const S_t& S, const Epi& E) {
;     ...
; #pragma unroll
;         for (int a = 0; a < 2; ++a)
; #pragma unroll
;             for (int b = 0; b < 2; ++b)
; #pragma unroll
;                 for (int m = 0; m < 4; ++m)
; #pragma unroll
;                     for (int n = 0; n < 2; ++n) acc[a][b][m][n] = (f32x4){0.f, 0.f, 0.f, 0.f};
;         cur = nxt; cA = nA; cB = nB; ++ui;
;     __device__ __forceinline__ void operator()(const f32x4 (&acc)[2][2][4][2], const Unit& u, int wr, int wc, int fr, int fq) const {
;     ...
;             const f32x4 wg0 = *(const f32x4*)(wconv + jc), wg1 = *(const f32x4*)(wconv + 2 * DFF + jc), wg2 = *(const f32x4*)(wconv + 4 * DFF + jc), bg = *(const f32x4*)(bconv + jc);
;             const f32x4 wv0 = *(const f32x4*)(wconv + DFF + jc), wv1 = *(const f32x4*)(wconv + 3 * DFF + jc), wv2 = *(const f32x4*)(wconv + 5 * DFF + jc), bv = *(const f32x4*)(bconv + DFF + jc);
.LBB0_1199:
	v_readlane_b32 s100, v254, 41
	v_readlane_b32 s101, v254, 42
	v_readlane_b32 s98, v254, 43
	v_readlane_b32 s99, v254, 44
	v_and_b32_e32 v128, 63, v212
	v_lshrrev_b32_e32 v129, 3, v128
	v_and_b32_e32 v128, 7, v128
	v_and_b32_e32 v130, 0x60, v219
	v_lshl_or_b32 v130, s42, 7, v130
	v_lshlrev_b32_e32 v130, 2, v130
	v_lshl_add_u32 v130, v128, 4, v130
	v_cmp_gt_u32_e32 vcc, 6, v129
	v_subrev_u32_e32 v131, 6, v129
	v_mov_b32_e32 v132, s100
	v_mov_b32_e32 v133, s98
	v_mov_b32_e32 v134, s101
	v_mov_b32_e32 v135, s99
	v_cndmask_b32_e32 v131, v131, v129, vcc
	v_cndmask_b32_e32 v132, v133, v132, vcc
	v_cndmask_b32_e32 v134, v135, v134, vcc
	v_mul_u32_u24_e32 v131, 0x6000, v131
	v_add_u32_e32 v130, v130, v131
	v_add_co_u32_e32 v130, vcc, v132, v130
	v_addc_co_u32_e32 v131, vcc, 0, v134, vcc
	v_readfirstlane_b32 s98, v212
	s_lshr_b32 s98, s98, 6
	s_lshl_b32 s98, s98, 10
	s_add_i32 m0, s98, 0x20840
	s_nop 0
	global_load_lds_dwordx4 v[130:131], off
	s_add_u32 s74, s74, 0x80080
	s_addc_u32 s75, s75, 0
	s_add_u32 s0, s76, 0x100
	s_addc_u32 s1, s77, 0
	s_mov_b32 s5, -2
	v_mov_b64_e32 v[0:1], 0
	v_mov_b64_e32 v[2:3], 0
	v_mov_b64_e32 v[4:5], 0
	v_mov_b64_e32 v[6:7], 0
	v_mov_b64_e32 v[8:9], 0
	v_mov_b64_e32 v[10:11], 0
	v_mov_b64_e32 v[12:13], 0
	v_mov_b64_e32 v[14:15], 0
	v_mov_b64_e32 v[16:17], 0
	v_mov_b64_e32 v[18:19], 0
	v_mov_b64_e32 v[20:21], 0
	v_mov_b64_e32 v[22:23], 0
	v_mov_b64_e32 v[24:25], 0
	v_mov_b64_e32 v[26:27], 0
	v_mov_b64_e32 v[28:29], 0
	v_mov_b64_e32 v[30:31], 0
	v_mov_b64_e32 v[32:33], 0
	v_mov_b64_e32 v[34:35], 0
	v_mov_b64_e32 v[36:37], 0
	v_mov_b64_e32 v[38:39], 0
	v_mov_b64_e32 v[40:41], 0
	v_mov_b64_e32 v[42:43], 0
	v_mov_b64_e32 v[44:45], 0
	v_mov_b64_e32 v[46:47], 0
	v_mov_b64_e32 v[48:49], 0
	v_mov_b64_e32 v[50:51], 0
	v_mov_b64_e32 v[52:53], 0
	v_mov_b64_e32 v[54:55], 0
	v_mov_b64_e32 v[56:57], 0
	v_mov_b64_e32 v[58:59], 0
	v_mov_b64_e32 v[60:61], 0
	v_mov_b64_e32 v[62:63], 0
	v_mov_b64_e32 v[64:65], 0
	v_mov_b64_e32 v[66:67], 0
	v_mov_b64_e32 v[68:69], 0
	v_mov_b64_e32 v[70:71], 0
	v_mov_b64_e32 v[72:73], 0
	v_mov_b64_e32 v[74:75], 0
	v_mov_b64_e32 v[76:77], 0
	v_mov_b64_e32 v[78:79], 0
	v_mov_b64_e32 v[80:81], 0
	v_mov_b64_e32 v[82:83], 0
	v_mov_b64_e32 v[84:85], 0
	v_mov_b64_e32 v[86:87], 0
	v_mov_b64_e32 v[88:89], 0
	v_mov_b64_e32 v[90:91], 0
	v_mov_b64_e32 v[92:93], 0
	v_mov_b64_e32 v[94:95], 0
	v_mov_b64_e32 v[96:97], 0
	v_mov_b64_e32 v[98:99], 0
	v_mov_b64_e32 v[100:101], 0
	v_mov_b64_e32 v[102:103], 0
	v_mov_b64_e32 v[104:105], 0
	v_mov_b64_e32 v[106:107], 0
	v_mov_b64_e32 v[108:109], 0
	v_mov_b64_e32 v[110:111], 0
	v_mov_b64_e32 v[112:113], 0
	v_mov_b64_e32 v[114:115], 0
	v_mov_b64_e32 v[116:117], 0
	v_mov_b64_e32 v[118:119], 0
	v_mov_b64_e32 v[120:121], 0
	v_mov_b64_e32 v[122:123], 0
	v_mov_b64_e32 v[124:125], 0
	v_mov_b64_e32 v[126:127], 0
	s_cmpk_gt_u32 s51, 0xff
	s_cbranch_scc1 .Lprio_b1200

;     __device__ __forceinline__ void operator()(const f32x4 (&acc)[2][2][4][2], const Unit& u, int wr, int wc, int fr, int fq) const {
;         const int row0 = u.pm * BM + wr * 64 + fr, col0 = u.pn * BM + wc * 32 + 8 * fq;
;         if (u.pm >= 32) {
; #pragma unroll
;             for (int ai = 0; ai < 2; ++ai)
; #pragma unroll
;                 for (int m = 0; m < 4; ++m) { bf16_t* rowp = UP + (size_t)(row0 + ai * HALF + m * 16) * (2 * DFF) + col0;
; #pragma unroll
;                     for (int bj = 0; bj < 2; ++bj) { const f32x4 v0 = acc[ai][bj][m][0], v1 = acc[ai][bj][m][1];
;                         u32x4 w; w.x = pk2(v0[0], v0[1]); w.y = pk2(v0[2], v0[3]); w.z = pk2(v1[0], v1[1]); w.w = pk2(v1[2], v1[3]);
;                         *(u32x4*)(rowp + bj * HALF) = w; } }
;             return;
;         }
;         const int j0 = u.pn * HALF + wc * 32 + 8 * fq;
;         u32x2 res0[8];
; #pragma unroll
;         for (int n = 0; n < 2; ++n) {
;             asm volatile("" ::: "memory");
;             const int jc = j0 + 4 * n;
;             const f32x4 wg0 = *(const f32x4*)(wconv + jc), wg1 = *(const f32x4*)(wconv + 2 * DFF + jc), wg2 = *(const f32x4*)(wconv + 4 * DFF + jc), bg = *(const f32x4*)(bconv + jc);
;             const f32x4 wv0 = *(const f32x4*)(wconv + DFF + jc), wv1 = *(const f32x4*)(wconv + 3 * DFF + jc), wv2 = *(const f32x4*)(wconv + 5 * DFF + jc), bv = *(const f32x4*)(bconv + DFF + jc);
; #pragma unroll
;             for (int ai = 0; ai < 2; ++ai)
; #pragma unroll
;                 for (int m = 0; m < 4; ++m) { const int row = row0 + ai * HALF + m * 16;
;                     const f32x4 g0 = acc[ai][0][m][n], v0 = acc[ai][1][m][n];
;                     f32x4 gp = (f32x4){0.f, 0.f, 0.f, 0.f}, vp = gp;
;                     if (m > 0) { gp = acc[ai][0][m > 0 ? m - 1 : 0][n]; vp = acc[ai][1][m > 0 ? m - 1 : 0][n]; }
;                     f32x4 f;
; #pragma unroll
;                     for (int j = 0; j < 4; ++j) {
;                         const float g1 = dpp_shr1(dpp_ror1(gp[j]), g0[j]), g2 = dpp_shr2(dpp_ror2(gp[j]), g0[j]);
;                         const float v1 = dpp_shr1(dpp_ror1(vp[j]), v0[j]), v2 = dpp_shr2(dpp_ror2(vp[j]), v0[j]);
;                         const float cg_ = bg[j] + g2 * wg0[j] + g1 * wg1[j] + g0[j] * wg2[j];
;                         const float cv_ = bv[j] + v2 * wv0[j] + v1 * wv1[j] + v0[j] * wv2[j];
.Lprio_x1200:
	s_lshl_b32 s5, s72, 8
	s_add_i32 s5, s5, s95
	v_or_b32_e32 v248, s5, v232
	s_cmp_lt_i32 s72, 32
	v_lshl_or_b32 v240, s42, 8, v219
	s_cbranch_scc0 .LBB0_1215
	v_lshl_or_b32 v130, s42, 7, v219
	v_readlane_b32 s16, v254, 33
	v_readlane_b32 s17, v254, 34
	v_readlane_b32 s18, v254, 35
	v_readlane_b32 s19, v254, 36
	v_readlane_b32 s20, v254, 37
	v_readlane_b32 s21, v254, 38
	v_readlane_b32 s22, v254, 39
	v_readlane_b32 s23, v254, 40
	v_readlane_b32 s24, v254, 41
	v_readlane_b32 s25, v254, 42
	v_readlane_b32 s26, v254, 43
	v_readlane_b32 s27, v254, 44
	v_readlane_b32 s28, v254, 45
	v_readlane_b32 s29, v254, 46
	v_readlane_b32 s30, v254, 47
	v_readlane_b32 s31, v254, 48
	v_ashrrev_i32_e32 v131, 31, v130
	s_ashr_i32 s72, s5, 6
	v_lshlrev_b64 v[128:129], 2, v[130:131]
	s_lshl_b32 s72, s72, 2
	s_add_i32 s73, s72, 8
	v_readfirstlane_b32 s98, v212
	v_and_b32_e32 v249, 48, v212
	s_lshr_b32 s98, s98, 6
	s_lshl_b32 s98, s98, 10
	s_add_i32 s98, s98, 0x20840
	v_lshl_add_u32 v249, v249, 1, s98
	ds_read_b128 v[146:149], v249 offset:768
	ds_read_b128 v[178:181], v249 offset:784
	ds_read_b128 v[158:161], v249 offset:512
	ds_read_b128 v[190:193], v249 offset:528
	ds_read_b128 v[162:165], v249 offset:896
	ds_read_b128 v[194:197], v249 offset:912
	ds_read_b128 v[174:177], v249 offset:640
	ds_read_b128 v[206:209], v249 offset:656
	ds_read_b128 v[154:157], v249 offset:256
	ds_read_b128 v[186:189], v249 offset:272
	ds_read_b128 v[170:173], v249 offset:384
	ds_read_b128 v[202:205], v249 offset:400
	ds_read_b128 v[150:153], v249 offset:0
	ds_read_b128 v[182:185], v249 offset:16
	ds_read_b128 v[166:169], v249 offset:128
	ds_read_b128 v[198:201], v249 offset:144
	v_lshl_add_u64 v[242:243], v[130:131], 1, s[40:41]
	v_ashrrev_i32_e32 v241, 31, v240
	s_mov_b32 s98, 0xbdd2d3e8
	s_mov_b32 s99, 0xbdd2d3e8
	s_mov_b32 s100, 1.0
	s_mov_b32 s101, 1.0
	v_mov_b32_e32 v244, 0xc0135761
	v_mov_b32_e32 v245, 0xc0135761
	s_and_saveexec_b64 s[42:43], s[10:11]
	v_or_b32_e32 v144, s72, v232
	v_mov_b64_e32 v[128:129], s[80:81]
	v_mad_u64_u32 v[128:129], vcc, v144, s83, v[128:129]
	v_lshl_add_u64 v[128:129], v[240:241], 1, v[128:129]
	v_cvt_pk_bf16_f32 v132, v124, v125
	v_cvt_pk_bf16_f32 v133, v126, v127
	v_cvt_pk_bf16_f32 v134, v120, v121
	v_cvt_pk_bf16_f32 v135, v122, v123
	v_cvt_pk_bf16_f32 v136, v112, v113
	v_cvt_pk_bf16_f32 v137, v114, v115
	v_cvt_pk_bf16_f32 v138, v104, v105
	v_cvt_pk_bf16_f32 v139, v106, v107
	global_store_dwordx4 v[128:129], v[132:135], off
	global_store_dwordx4 v[128:129], v[136:139], off offset:256
	v_or_b32_e32 v144, s73, v232
	v_mov_b64_e32 v[130:131], s[80:81]
	v_mad_u64_u32 v[130:131], vcc, v144, s83, v[130:131]
	v_lshl_add_u64 v[130:131], v[240:241], 1, v[130:131]
	v_cvt_pk_bf16_f32 v140, v60, v61
	v_cvt_pk_bf16_f32 v141, v62, v63
	v_cvt_pk_bf16_f32 v142, v56, v57
	v_cvt_pk_bf16_f32 v143, v58, v59
	v_cvt_pk_bf16_f32 v250, v48, v49
	v_cvt_pk_bf16_f32 v251, v50, v51
	v_cvt_pk_bf16_f32 v252, v40, v41
	v_cvt_pk_bf16_f32 v253, v42, v43
	global_store_dwordx4 v[130:131], v[140:143], off
	global_store_dwordx4 v[130:131], v[250:253], off offset:256
	s_or_b64 exec, exec, s[42:43]
	s_and_saveexec_b64 s[42:43], s[12:13]
	v_add_u32_e32 v144, s72, v234
	v_mov_b64_e32 v[128:129], s[80:81]
	v_mad_u64_u32 v[128:129], vcc, v144, s83, v[128:129]
	v_lshl_add_u64 v[128:129], v[240:241], 1, v[128:129]
	v_cvt_pk_bf16_f32 v132, v84, v85
	v_cvt_pk_bf16_f32 v133, v86, v87
	v_cvt_pk_bf16_f32 v134, v76, v77
	v_cvt_pk_bf16_f32 v135, v78, v79
	v_cvt_pk_bf16_f32 v136, v68, v69
	v_cvt_pk_bf16_f32 v137, v70, v71
	v_cvt_pk_bf16_f32 v138, v64, v65
	v_cvt_pk_bf16_f32 v139, v66, v67
	global_store_dwordx4 v[128:129], v[132:135], off
	global_store_dwordx4 v[128:129], v[136:139], off offset:256
	s_or_b64 exec, exec, s[42:43]
	s_waitcnt lgkmcnt(0)
	s_nop 4
	v_pk_fma_f32 v[132:133], v[124:125], v[158:159], v[146:147]
	v_pk_fma_f32 v[136:137], v[112:113], v[174:175], v[162:163]
	v_pk_fma_f32 v[134:135], v[126:127], v[160:161], v[148:149]
	v_pk_fma_f32 v[138:139], v[114:115], v[176:177], v[164:165]
	v_fmac_f32_dpp v132, v124, v154 row_shr:1 row_mask:0xf bank_mask:0xf
	v_fmac_f32_dpp v133, v125, v155 row_shr:1 row_mask:0xf bank_mask:0xf
	v_fmac_f32_dpp v134, v126, v156 row_shr:1 row_mask:0xf bank_mask:0xf
	v_fmac_f32_dpp v135, v127, v157 row_shr:1 row_mask:0xf bank_mask:0xf
	v_fmac_f32_dpp v136, v112, v170 row_shr:1 row_mask:0xf bank_mask:0xf
	v_fmac_f32_dpp v137, v113, v171 row_shr:1 row_mask:0xf bank_mask:0xf
	v_fmac_f32_dpp v138, v114, v172 row_shr:1 row_mask:0xf bank_mask:0xf
	v_fmac_f32_dpp v139, v115, v173 row_shr:1 row_mask:0xf bank_mask:0xf
	v_fmac_f32_dpp v132, v124, v150 row_shr:2 row_mask:0xf bank_mask:0xf
	v_fmac_f32_dpp v133, v125, v151 row_shr:2 row_mask:0xf bank_mask:0xf
	v_fmac_f32_dpp v134, v126, v152 row_shr:2 row_mask:0xf bank_mask:0xf
	v_fmac_f32_dpp v135, v127, v153 row_shr:2 row_mask:0xf bank_mask:0xf
	v_fmac_f32_dpp v136, v112, v166 row_shr:2 row_mask:0xf bank_mask:0xf
	v_fmac_f32_dpp v137, v113, v167 row_shr:2 row_mask:0xf bank_mask:0xf
	v_fmac_f32_dpp v138, v114, v168 row_shr:2 row_mask:0xf bank_mask:0xf
	v_fmac_f32_dpp v139, v115, v169 row_shr:2 row_mask:0xf bank_mask:0xf
	v_pk_mul_f32 v[140:141], v[132:133], v[132:133]
	v_pk_mul_f32 v[142:143], v[134:135], v[134:135]
	v_pk_fma_f32 v[140:141], v[140:141], s[98:99], v[244:245]
	v_pk_fma_f32 v[142:143], v[142:143], s[98:99], v[244:245]
	v_pk_mul_f32 v[140:141], v[132:133], v[140:141]
	v_pk_mul_f32 v[142:143], v[134:135], v[142:143]
	v_exp_f32_e32 v140, v140
	v_exp_f32_e32 v141, v141
	v_exp_f32_e32 v142, v142
	v_exp_f32_e32 v143, v143
	v_pk_add_f32 v[140:141], v[140:141], s[100:101]
	v_pk_add_f32 v[142:143], v[142:143], s[100:101]
; __device__ __forceinline__ unsigned pk2(float lo, float hi) { unsigned r; asm("v_cvt_pk_bf16_f32 %0, %1, %2" : "=v"(r) : "v"(lo), "v"(hi)); return r; }
;     __device__ __forceinline__ void operator()(const f32x4 (&acc)[2][2][4][2], const Unit& u, int wr, int wc, int fr, int fq) const {
;     ...
; #pragma unroll
;             for (int ai = 0; ai < 2; ++ai)
; #pragma unroll
;                 for (int m = 0; m < 4; ++m) { const int row = row0 + ai * HALF + m * 16;
;                     const f32x4 g0 = acc[ai][0][m][n], v0 = acc[ai][1][m][n];
;                     f32x4 gp = (f32x4){0.f, 0.f, 0.f, 0.f}, vp = gp;
;                     if (m > 0) { gp = acc[ai][0][m > 0 ? m - 1 : 0][n]; vp = acc[ai][1][m > 0 ? m - 1 : 0][n]; }
;                     f32x4 f;
; #pragma unroll
;                     for (int j = 0; j < 4; ++j) {
;                         const float g1 = dpp_shr1(dpp_ror1(gp[j]), g0[j]), g2 = dpp_shr2(dpp_ror2(gp[j]), g0[j]);
;                         const float v1 = dpp_shr1(dpp_ror1(vp[j]), v0[j]), v2 = dpp_shr2(dpp_ror2(vp[j]), v0[j]);
;                         const float cg_ = bg[j] + g2 * wg0[j] + g1 * wg1[j] + g0[j] * wg2[j];
;                         const float cv_ = bv[j] + v2 * wv0[j] + v1 * wv1[j] + v0[j] * wv2[j];
;                         f[j] = gelu_tanh(cg_) * cv_; }
;                     u32x2 w; w.x = pk2(f[0], f[1]); w.y = pk2(f[2], f[3]);
;                     if (n == 0) res0[ai * 4 + m] = w;
;                     else if (m > 0 || fr >= 2) { u32x4 w4; w4.x = res0[ai * 4 + m].x; w4.y = res0[ai * 4 + m].y; w4.z = w.x; w4.w = w.y; *(u32x4*)(F + (size_t)row * DFF + j0) = w4; }
;                     if (n == 1 && ((m == 0 && fr < 2) || (m == 3 && fr >= 14))) { const int slot = m == 0 ? fr : fr - 12;
;                         const f32x4 ga = acc[ai][0][m][0], va = acc[ai][1][m][0];
;                         bf16_t* bp = UPB + ((size_t)(row >> 6) * 4 + slot) * (2 * DFF) + col0;
;                         u32x4 wg_, wv_; wg_.x = pk2(ga[0], ga[1]); wg_.y = pk2(ga[2], ga[3]); wg_.z = pk2(g0[0], g0[1]); wg_.w = pk2(g0[2], g0[3]);
;                         wv_.x = pk2(va[0], va[1]); wv_.y = pk2(va[2], va[3]); wv_.z = pk2(v0[0], v0[1]); wv_.w = pk2(v0[2], v0[3]);
;                         *(u32x4*)bp = wg_; *(u32x4*)(bp + HALF) = wv_; } }
	v_rcp_f32_e32 v140, v140
	v_rcp_f32_e32 v141, v141
	v_rcp_f32_e32 v142, v142
	v_rcp_f32_e32 v143, v143
	v_pk_mul_f32 v[140:141], v[132:133], v[140:141]
	v_pk_mul_f32 v[142:143], v[134:135], v[142:143]
	v_pk_mul_f32 v[140:141], v[140:141], v[136:137]
	v_pk_mul_f32 v[142:143], v[142:143], v[138:139]
	v_cvt_pk_bf16_f32 v128, v140, v141
	v_cvt_pk_bf16_f32 v129, v142, v143
	v_pk_fma_f32 v[132:133], v[120:121], v[190:191], v[178:179]
	v_pk_fma_f32 v[136:137], v[104:105], v[206:207], v[194:195]
	v_pk_fma_f32 v[134:135], v[122:123], v[192:193], v[180:181]
	v_pk_fma_f32 v[138:139], v[106:107], v[208:209], v[196:197]
	v_fmac_f32_dpp v132, v120, v186 row_shr:1 row_mask:0xf bank_mask:0xf
	v_fmac_f32_dpp v133, v121, v187 row_shr:1 row_mask:0xf bank_mask:0xf
	v_fmac_f32_dpp v134, v122, v188 row_shr:1 row_mask:0xf bank_mask:0xf
	v_fmac_f32_dpp v135, v123, v189 row_shr:1 row_mask:0xf bank_mask:0xf
	v_fmac_f32_dpp v136, v104, v202 row_shr:1 row_mask:0xf bank_mask:0xf
	v_fmac_f32_dpp v137, v105, v203 row_shr:1 row_mask:0xf bank_mask:0xf
	v_fmac_f32_dpp v138, v106, v204 row_shr:1 row_mask:0xf bank_mask:0xf
	v_fmac_f32_dpp v139, v107, v205 row_shr:1 row_mask:0xf bank_mask:0xf
	v_fmac_f32_dpp v132, v120, v182 row_shr:2 row_mask:0xf bank_mask:0xf
	v_fmac_f32_dpp v133, v121, v183 row_shr:2 row_mask:0xf bank_mask:0xf
	v_fmac_f32_dpp v134, v122, v184 row_shr:2 row_mask:0xf bank_mask:0xf
	v_fmac_f32_dpp v135, v123, v185 row_shr:2 row_mask:0xf bank_mask:0xf
	v_fmac_f32_dpp v136, v104, v198 row_shr:2 row_mask:0xf bank_mask:0xf
	v_fmac_f32_dpp v137, v105, v199 row_shr:2 row_mask:0xf bank_mask:0xf
	v_fmac_f32_dpp v138, v106, v200 row_shr:2 row_mask:0xf bank_mask:0xf
	v_fmac_f32_dpp v139, v107, v201 row_shr:2 row_mask:0xf bank_mask:0xf
	v_pk_mul_f32 v[140:141], v[132:133], v[132:133]
	v_pk_mul_f32 v[142:143], v[134:135], v[134:135]
	v_pk_fma_f32 v[140:141], v[140:141], s[98:99], v[244:245]
	v_pk_fma_f32 v[142:143], v[142:143], s[98:99], v[244:245]
	v_pk_mul_f32 v[140:141], v[132:133], v[140:141]
	v_pk_mul_f32 v[142:143], v[134:135], v[142:143]
	v_exp_f32_e32 v140, v140
	v_exp_f32_e32 v141, v141
	v_exp_f32_e32 v142, v142
	v_exp_f32_e32 v143, v143
	v_pk_add_f32 v[140:141], v[140:141], s[100:101]
	v_pk_add_f32 v[142:143], v[142:143], s[100:101]
	v_rcp_f32_e32 v140, v140
	v_rcp_f32_e32 v141, v141
	v_rcp_f32_e32 v142, v142
	v_rcp_f32_e32 v143, v143
	v_pk_mul_f32 v[140:141], v[132:133], v[140:141]
	v_pk_mul_f32 v[142:143], v[134:135], v[142:143]
	v_pk_mul_f32 v[140:141], v[140:141], v[136:137]
	v_pk_mul_f32 v[142:143], v[142:143], v[138:139]
	v_cvt_pk_bf16_f32 v130, v140, v141
	v_cvt_pk_bf16_f32 v131, v142, v143
	s_and_saveexec_b64 s[42:43], s[8:9]
	v_mad_u64_u32 v[144:145], vcc, v248, s4, v[242:243]
	global_store_dwordx4 v[144:145], v[128:131], off nt
	s_or_b64 exec, exec, s[42:43]
	s_nop 4
	v_pk_fma_f32 v[132:133], v[116:117], v[158:159], v[146:147]
	v_pk_fma_f32 v[136:137], v[96:97], v[174:175], v[162:163]
	v_pk_fma_f32 v[134:135], v[118:119], v[160:161], v[148:149]
	v_pk_fma_f32 v[138:139], v[98:99], v[176:177], v[164:165]
	v_fmac_f32_dpp v132, v116, v154 row_shr:1 row_mask:0xf bank_mask:0xf
	v_fmac_f32_dpp v133, v117, v155 row_shr:1 row_mask:0xf bank_mask:0xf
	v_fmac_f32_dpp v134, v118, v156 row_shr:1 row_mask:0xf bank_mask:0xf
	v_fmac_f32_dpp v135, v119, v157 row_shr:1 row_mask:0xf bank_mask:0xf
	v_fmac_f32_dpp v136, v96, v170 row_shr:1 row_mask:0xf bank_mask:0xf
	v_fmac_f32_dpp v137, v97, v171 row_shr:1 row_mask:0xf bank_mask:0xf
	v_fmac_f32_dpp v138, v98, v172 row_shr:1 row_mask:0xf bank_mask:0xf
	v_fmac_f32_dpp v139, v99, v173 row_shr:1 row_mask:0xf bank_mask:0xf
	v_fmac_f32_dpp v132, v124, v154 row_shl:15 row_mask:0xf bank_mask:0xf
	v_fmac_f32_dpp v133, v125, v155 row_shl:15 row_mask:0xf bank_mask:0xf
	v_fmac_f32_dpp v134, v126, v156 row_shl:15 row_mask:0xf bank_mask:0xf
	v_fmac_f32_dpp v135, v127, v157 row_shl:15 row_mask:0xf bank_mask:0xf
	v_fmac_f32_dpp v136, v112, v170 row_shl:15 row_mask:0xf bank_mask:0xf
	v_fmac_f32_dpp v137, v113, v171 row_shl:15 row_mask:0xf bank_mask:0xf
	v_fmac_f32_dpp v138, v114, v172 row_shl:15 row_mask:0xf bank_mask:0xf
	v_fmac_f32_dpp v139, v115, v173 row_shl:15 row_mask:0xf bank_mask:0xf
	v_fmac_f32_dpp v132, v116, v150 row_shr:2 row_mask:0xf bank_mask:0xf
	v_fmac_f32_dpp v133, v117, v151 row_shr:2 row_mask:0xf bank_mask:0xf
	v_fmac_f32_dpp v134, v118, v152 row_shr:2 row_mask:0xf bank_mask:0xf
	v_fmac_f32_dpp v135, v119, v153 row_shr:2 row_mask:0xf bank_mask:0xf
	v_fmac_f32_dpp v136, v96, v166 row_shr:2 row_mask:0xf bank_mask:0xf
	v_fmac_f32_dpp v137, v97, v167 row_shr:2 row_mask:0xf bank_mask:0xf
	v_fmac_f32_dpp v138, v98, v168 row_shr:2 row_mask:0xf bank_mask:0xf
	v_fmac_f32_dpp v139, v99, v169 row_shr:2 row_mask:0xf bank_mask:0xf
	v_fmac_f32_dpp v132, v124, v150 row_shl:14 row_mask:0xf bank_mask:0xf
	v_fmac_f32_dpp v133, v125, v151 row_shl:14 row_mask:0xf bank_mask:0xf
	v_fmac_f32_dpp v134, v126, v152 row_shl:14 row_mask:0xf bank_mask:0xf
	v_fmac_f32_dpp v135, v127, v153 row_shl:14 row_mask:0xf bank_mask:0xf
	v_fmac_f32_dpp v136, v112, v166 row_shl:14 row_mask:0xf bank_mask:0xf
	v_fmac_f32_dpp v137, v113, v167 row_shl:14 row_mask:0xf bank_mask:0xf
	v_fmac_f32_dpp v138, v114, v168 row_shl:14 row_mask:0xf bank_mask:0xf
	v_fmac_f32_dpp v139, v115, v169 row_shl:14 row_mask:0xf bank_mask:0xf
	v_pk_mul_f32 v[140:141], v[132:133], v[132:133]
	v_pk_mul_f32 v[142:143], v[134:135], v[134:135]
	v_pk_fma_f32 v[140:141], v[140:141], s[98:99], v[244:245]
	v_pk_fma_f32 v[142:143], v[142:143], s[98:99], v[244:245]
	v_pk_mul_f32 v[140:141], v[132:133], v[140:141]
	v_pk_mul_f32 v[142:143], v[134:135], v[142:143]
	v_exp_f32_e32 v140, v140
; __device__ __forceinline__ unsigned pk2(float lo, float hi) { unsigned r; asm("v_cvt_pk_bf16_f32 %0, %1, %2" : "=v"(r) : "v"(lo), "v"(hi)); return r; }
;     __device__ __forceinline__ void operator()(const f32x4 (&acc)[2][2][4][2], const Unit& u, int wr, int wc, int fr, int fq) const {
;     ...
; #pragma unroll
;             for (int ai = 0; ai < 2; ++ai)
; #pragma unroll
;                 for (int m = 0; m < 4; ++m) { const int row = row0 + ai * HALF + m * 16;
;                     const f32x4 g0 = acc[ai][0][m][n], v0 = acc[ai][1][m][n];
;                     f32x4 gp = (f32x4){0.f, 0.f, 0.f, 0.f}, vp = gp;
;                     if (m > 0) { gp = acc[ai][0][m > 0 ? m - 1 : 0][n]; vp = acc[ai][1][m > 0 ? m - 1 : 0][n]; }
;                     f32x4 f;
; #pragma unroll
;                     for (int j = 0; j < 4; ++j) {
;                         const float g1 = dpp_shr1(dpp_ror1(gp[j]), g0[j]), g2 = dpp_shr2(dpp_ror2(gp[j]), g0[j]);
;                         const float v1 = dpp_shr1(dpp_ror1(vp[j]), v0[j]), v2 = dpp_shr2(dpp_ror2(vp[j]), v0[j]);
;                         const float cg_ = bg[j] + g2 * wg0[j] + g1 * wg1[j] + g0[j] * wg2[j];
;                         const float cv_ = bv[j] + v2 * wv0[j] + v1 * wv1[j] + v0[j] * wv2[j];
;                         f[j] = gelu_tanh(cg_) * cv_; }
;                     u32x2 w; w.x = pk2(f[0], f[1]); w.y = pk2(f[2], f[3]);
;                     if (n == 0) res0[ai * 4 + m] = w;
;                     else if (m > 0 || fr >= 2) { u32x4 w4; w4.x = res0[ai * 4 + m].x; w4.y = res0[ai * 4 + m].y; w4.z = w.x; w4.w = w.y; *(u32x4*)(F + (size_t)row * DFF + j0) = w4; }
;                     if (n == 1 && ((m == 0 && fr < 2) || (m == 3 && fr >= 14))) { const int slot = m == 0 ? fr : fr - 12;
;                         const f32x4 ga = acc[ai][0][m][0], va = acc[ai][1][m][0];
;                         bf16_t* bp = UPB + ((size_t)(row >> 6) * 4 + slot) * (2 * DFF) + col0;
;                         u32x4 wg_, wv_; wg_.x = pk2(ga[0], ga[1]); wg_.y = pk2(ga[2], ga[3]); wg_.z = pk2(g0[0], g0[1]); wg_.w = pk2(g0[2], g0[3]);
;                         wv_.x = pk2(va[0], va[1]); wv_.y = pk2(va[2], va[3]); wv_.z = pk2(v0[0], v0[1]); wv_.w = pk2(v0[2], v0[3]);
;                         *(u32x4*)bp = wg_; *(u32x4*)(bp + HALF) = wv_; } }
	v_exp_f32_e32 v141, v141
	v_exp_f32_e32 v142, v142
	v_exp_f32_e32 v143, v143
	v_pk_add_f32 v[140:141], v[140:141], s[100:101]
	v_pk_add_f32 v[142:143], v[142:143], s[100:101]
	v_rcp_f32_e32 v140, v140
	v_rcp_f32_e32 v141, v141
	v_rcp_f32_e32 v142, v142
	v_rcp_f32_e32 v143, v143
	v_pk_mul_f32 v[140:141], v[132:133], v[140:141]
	v_pk_mul_f32 v[142:143], v[134:135], v[142:143]
	v_pk_mul_f32 v[140:141], v[140:141], v[136:137]
	v_pk_mul_f32 v[142:143], v[142:143], v[138:139]
	v_cvt_pk_bf16_f32 v250, v140, v141
	v_cvt_pk_bf16_f32 v251, v142, v143
	v_pk_fma_f32 v[132:133], v[108:109], v[190:191], v[178:179]
	v_pk_fma_f32 v[136:137], v[88:89], v[206:207], v[194:195]
	v_pk_fma_f32 v[134:135], v[110:111], v[192:193], v[180:181]
	v_pk_fma_f32 v[138:139], v[90:91], v[208:209], v[196:197]
	v_fmac_f32_dpp v132, v108, v186 row_shr:1 row_mask:0xf bank_mask:0xf
	v_fmac_f32_dpp v133, v109, v187 row_shr:1 row_mask:0xf bank_mask:0xf
	v_fmac_f32_dpp v134, v110, v188 row_shr:1 row_mask:0xf bank_mask:0xf
	v_fmac_f32_dpp v135, v111, v189 row_shr:1 row_mask:0xf bank_mask:0xf
	v_fmac_f32_dpp v136, v88, v202 row_shr:1 row_mask:0xf bank_mask:0xf
	v_fmac_f32_dpp v137, v89, v203 row_shr:1 row_mask:0xf bank_mask:0xf
	v_fmac_f32_dpp v138, v90, v204 row_shr:1 row_mask:0xf bank_mask:0xf
	v_fmac_f32_dpp v139, v91, v205 row_shr:1 row_mask:0xf bank_mask:0xf
	v_fmac_f32_dpp v132, v120, v186 row_shl:15 row_mask:0xf bank_mask:0xf
	v_fmac_f32_dpp v133, v121, v187 row_shl:15 row_mask:0xf bank_mask:0xf
	v_fmac_f32_dpp v134, v122, v188 row_shl:15 row_mask:0xf bank_mask:0xf
	v_fmac_f32_dpp v135, v123, v189 row_shl:15 row_mask:0xf bank_mask:0xf
	v_fmac_f32_dpp v136, v104, v202 row_shl:15 row_mask:0xf bank_mask:0xf
	v_fmac_f32_dpp v137, v105, v203 row_shl:15 row_mask:0xf bank_mask:0xf
	v_fmac_f32_dpp v138, v106, v204 row_shl:15 row_mask:0xf bank_mask:0xf
	v_fmac_f32_dpp v139, v107, v205 row_shl:15 row_mask:0xf bank_mask:0xf
	v_fmac_f32_dpp v132, v108, v182 row_shr:2 row_mask:0xf bank_mask:0xf
	v_fmac_f32_dpp v133, v109, v183 row_shr:2 row_mask:0xf bank_mask:0xf
	v_fmac_f32_dpp v134, v110, v184 row_shr:2 row_mask:0xf bank_mask:0xf
	v_fmac_f32_dpp v135, v111, v185 row_shr:2 row_mask:0xf bank_mask:0xf
	v_fmac_f32_dpp v136, v88, v198 row_shr:2 row_mask:0xf bank_mask:0xf
	v_fmac_f32_dpp v137, v89, v199 row_shr:2 row_mask:0xf bank_mask:0xf
	v_fmac_f32_dpp v138, v90, v200 row_shr:2 row_mask:0xf bank_mask:0xf
	v_fmac_f32_dpp v139, v91, v201 row_shr:2 row_mask:0xf bank_mask:0xf
	v_fmac_f32_dpp v132, v120, v182 row_shl:14 row_mask:0xf bank_mask:0xf
	v_fmac_f32_dpp v133, v121, v183 row_shl:14 row_mask:0xf bank_mask:0xf
	v_fmac_f32_dpp v134, v122, v184 row_shl:14 row_mask:0xf bank_mask:0xf
	v_fmac_f32_dpp v135, v123, v185 row_shl:14 row_mask:0xf bank_mask:0xf
	v_fmac_f32_dpp v136, v104, v198 row_shl:14 row_mask:0xf bank_mask:0xf
	v_fmac_f32_dpp v137, v105, v199 row_shl:14 row_mask:0xf bank_mask:0xf
	v_fmac_f32_dpp v138, v106, v200 row_shl:14 row_mask:0xf bank_mask:0xf
	v_fmac_f32_dpp v139, v107, v201 row_shl:14 row_mask:0xf bank_mask:0xf
	v_pk_mul_f32 v[140:141], v[132:133], v[132:133]
	v_pk_mul_f32 v[142:143], v[134:135], v[134:135]
	v_pk_fma_f32 v[140:141], v[140:141], s[98:99], v[244:245]
	v_pk_fma_f32 v[142:143], v[142:143], s[98:99], v[244:245]
	v_pk_mul_f32 v[140:141], v[132:133], v[140:141]
	v_pk_mul_f32 v[142:143], v[134:135], v[142:143]
	v_exp_f32_e32 v140, v140
	v_exp_f32_e32 v141, v141
	v_exp_f32_e32 v142, v142
	v_exp_f32_e32 v143, v143
	v_pk_add_f32 v[140:141], v[140:141], s[100:101]
	v_pk_add_f32 v[142:143], v[142:143], s[100:101]
	v_rcp_f32_e32 v140, v140
	v_rcp_f32_e32 v141, v141
	v_rcp_f32_e32 v142, v142
	v_rcp_f32_e32 v143, v143
	v_pk_mul_f32 v[140:141], v[132:133], v[140:141]
	v_pk_mul_f32 v[142:143], v[134:135], v[142:143]
	v_pk_mul_f32 v[140:141], v[140:141], v[136:137]
	v_pk_mul_f32 v[142:143], v[142:143], v[138:139]
	v_cvt_pk_bf16_f32 v252, v140, v141
	v_cvt_pk_bf16_f32 v253, v142, v143
	v_add_u32_e32 v144, 0x10, v248
	v_mad_u64_u32 v[144:145], vcc, v144, s4, v[242:243]
	global_store_dwordx4 v[144:145], v[250:253], off nt
	v_pk_fma_f32 v[132:133], v[100:101], v[158:159], v[146:147]
	v_pk_fma_f32 v[136:137], v[80:81], v[174:175], v[162:163]
	v_pk_fma_f32 v[134:135], v[102:103], v[160:161], v[148:149]
	v_pk_fma_f32 v[138:139], v[82:83], v[176:177], v[164:165]
	v_fmac_f32_dpp v132, v100, v154 row_shr:1 row_mask:0xf bank_mask:0xf
	v_fmac_f32_dpp v133, v101, v155 row_shr:1 row_mask:0xf bank_mask:0xf
	v_fmac_f32_dpp v134, v102, v156 row_shr:1 row_mask:0xf bank_mask:0xf
	v_fmac_f32_dpp v135, v103, v157 row_shr:1 row_mask:0xf bank_mask:0xf
	v_fmac_f32_dpp v136, v80, v170 row_shr:1 row_mask:0xf bank_mask:0xf
	v_fmac_f32_dpp v137, v81, v171 row_shr:1 row_mask:0xf bank_mask:0xf
	v_fmac_f32_dpp v138, v82, v172 row_shr:1 row_mask:0xf bank_mask:0xf
	v_fmac_f32_dpp v139, v83, v173 row_shr:1 row_mask:0xf bank_mask:0xf
	v_fmac_f32_dpp v132, v116, v154 row_shl:15 row_mask:0xf bank_mask:0xf
	v_fmac_f32_dpp v133, v117, v155 row_shl:15 row_mask:0xf bank_mask:0xf
	v_fmac_f32_dpp v134, v118, v156 row_shl:15 row_mask:0xf bank_mask:0xf
	v_fmac_f32_dpp v135, v119, v157 row_shl:15 row_mask:0xf bank_mask:0xf
	v_fmac_f32_dpp v136, v96, v170 row_shl:15 row_mask:0xf bank_mask:0xf
	v_fmac_f32_dpp v137, v97, v171 row_shl:15 row_mask:0xf bank_mask:0xf
	v_fmac_f32_dpp v138, v98, v172 row_shl:15 row_mask:0xf bank_mask:0xf
	v_fmac_f32_dpp v139, v99, v173 row_shl:15 row_mask:0xf bank_mask:0xf
	v_fmac_f32_dpp v132, v100, v150 row_shr:2 row_mask:0xf bank_mask:0xf
	v_fmac_f32_dpp v133, v101, v151 row_shr:2 row_mask:0xf bank_mask:0xf
	v_fmac_f32_dpp v134, v102, v152 row_shr:2 row_mask:0xf bank_mask:0xf
; __device__ __forceinline__ unsigned pk2(float lo, float hi) { unsigned r; asm("v_cvt_pk_bf16_f32 %0, %1, %2" : "=v"(r) : "v"(lo), "v"(hi)); return r; }
;     __device__ __forceinline__ void operator()(const f32x4 (&acc)[2][2][4][2], const Unit& u, int wr, int wc, int fr, int fq) const {
;     ...
; #pragma unroll
;             for (int ai = 0; ai < 2; ++ai)
; #pragma unroll
;                 for (int m = 0; m < 4; ++m) { const int row = row0 + ai * HALF + m * 16;
;                     const f32x4 g0 = acc[ai][0][m][n], v0 = acc[ai][1][m][n];
;                     f32x4 gp = (f32x4){0.f, 0.f, 0.f, 0.f}, vp = gp;
;                     if (m > 0) { gp = acc[ai][0][m > 0 ? m - 1 : 0][n]; vp = acc[ai][1][m > 0 ? m - 1 : 0][n]; }
;                     f32x4 f;
; #pragma unroll
;                     for (int j = 0; j < 4; ++j) {
;                         const float g1 = dpp_shr1(dpp_ror1(gp[j]), g0[j]), g2 = dpp_shr2(dpp_ror2(gp[j]), g0[j]);
;                         const float v1 = dpp_shr1(dpp_ror1(vp[j]), v0[j]), v2 = dpp_shr2(dpp_ror2(vp[j]), v0[j]);
;                         const float cg_ = bg[j] + g2 * wg0[j] + g1 * wg1[j] + g0[j] * wg2[j];
;                         const float cv_ = bv[j] + v2 * wv0[j] + v1 * wv1[j] + v0[j] * wv2[j];
;                         f[j] = gelu_tanh(cg_) * cv_; }
;                     u32x2 w; w.x = pk2(f[0], f[1]); w.y = pk2(f[2], f[3]);
;                     if (n == 0) res0[ai * 4 + m] = w;
;                     else if (m > 0 || fr >= 2) { u32x4 w4; w4.x = res0[ai * 4 + m].x; w4.y = res0[ai * 4 + m].y; w4.z = w.x; w4.w = w.y; *(u32x4*)(F + (size_t)row * DFF + j0) = w4; }
;                     if (n == 1 && ((m == 0 && fr < 2) || (m == 3 && fr >= 14))) { const int slot = m == 0 ? fr : fr - 12;
;                         const f32x4 ga = acc[ai][0][m][0], va = acc[ai][1][m][0];
;                         bf16_t* bp = UPB + ((size_t)(row >> 6) * 4 + slot) * (2 * DFF) + col0;
;                         u32x4 wg_, wv_; wg_.x = pk2(ga[0], ga[1]); wg_.y = pk2(ga[2], ga[3]); wg_.z = pk2(g0[0], g0[1]); wg_.w = pk2(g0[2], g0[3]);
;                         wv_.x = pk2(va[0], va[1]); wv_.y = pk2(va[2], va[3]); wv_.z = pk2(v0[0], v0[1]); wv_.w = pk2(v0[2], v0[3]);
;                         *(u32x4*)bp = wg_; *(u32x4*)(bp + HALF) = wv_; } }
	v_fmac_f32_dpp v135, v103, v153 row_shr:2 row_mask:0xf bank_mask:0xf
	v_fmac_f32_dpp v136, v80, v166 row_shr:2 row_mask:0xf bank_mask:0xf
	v_fmac_f32_dpp v137, v81, v167 row_shr:2 row_mask:0xf bank_mask:0xf
	v_fmac_f32_dpp v138, v82, v168 row_shr:2 row_mask:0xf bank_mask:0xf
	v_fmac_f32_dpp v139, v83, v169 row_shr:2 row_mask:0xf bank_mask:0xf
	v_fmac_f32_dpp v132, v116, v150 row_shl:14 row_mask:0xf bank_mask:0xf
	v_fmac_f32_dpp v133, v117, v151 row_shl:14 row_mask:0xf bank_mask:0xf
	v_fmac_f32_dpp v134, v118, v152 row_shl:14 row_mask:0xf bank_mask:0xf
	v_fmac_f32_dpp v135, v119, v153 row_shl:14 row_mask:0xf bank_mask:0xf
	v_fmac_f32_dpp v136, v96, v166 row_shl:14 row_mask:0xf bank_mask:0xf
	v_fmac_f32_dpp v137, v97, v167 row_shl:14 row_mask:0xf bank_mask:0xf
	v_fmac_f32_dpp v138, v98, v168 row_shl:14 row_mask:0xf bank_mask:0xf
	v_fmac_f32_dpp v139, v99, v169 row_shl:14 row_mask:0xf bank_mask:0xf
	v_pk_mul_f32 v[140:141], v[132:133], v[132:133]
	v_pk_mul_f32 v[142:143], v[134:135], v[134:135]
	v_pk_fma_f32 v[140:141], v[140:141], s[98:99], v[244:245]
	v_pk_fma_f32 v[142:143], v[142:143], s[98:99], v[244:245]
	v_pk_mul_f32 v[140:141], v[132:133], v[140:141]
	v_pk_mul_f32 v[142:143], v[134:135], v[142:143]
	v_exp_f32_e32 v140, v140
	v_exp_f32_e32 v141, v141
	v_exp_f32_e32 v142, v142
	v_exp_f32_e32 v143, v143
	v_pk_add_f32 v[140:141], v[140:141], s[100:101]
	v_pk_add_f32 v[142:143], v[142:143], s[100:101]
	v_rcp_f32_e32 v140, v140
	v_rcp_f32_e32 v141, v141
	v_rcp_f32_e32 v142, v142
	v_rcp_f32_e32 v143, v143
	v_pk_mul_f32 v[140:141], v[132:133], v[140:141]
	v_pk_mul_f32 v[142:143], v[134:135], v[142:143]
	v_pk_mul_f32 v[140:141], v[140:141], v[136:137]
	v_pk_mul_f32 v[142:143], v[142:143], v[138:139]
	v_cvt_pk_bf16_f32 v128, v140, v141
	v_cvt_pk_bf16_f32 v129, v142, v143
	v_pk_fma_f32 v[132:133], v[92:93], v[190:191], v[178:179]
	v_pk_fma_f32 v[136:137], v[72:73], v[206:207], v[194:195]
	v_pk_fma_f32 v[134:135], v[94:95], v[192:193], v[180:181]
	v_pk_fma_f32 v[138:139], v[74:75], v[208:209], v[196:197]
	v_fmac_f32_dpp v132, v92, v186 row_shr:1 row_mask:0xf bank_mask:0xf
	v_fmac_f32_dpp v133, v93, v187 row_shr:1 row_mask:0xf bank_mask:0xf
	v_fmac_f32_dpp v134, v94, v188 row_shr:1 row_mask:0xf bank_mask:0xf
	v_fmac_f32_dpp v135, v95, v189 row_shr:1 row_mask:0xf bank_mask:0xf
	v_fmac_f32_dpp v136, v72, v202 row_shr:1 row_mask:0xf bank_mask:0xf
	v_fmac_f32_dpp v137, v73, v203 row_shr:1 row_mask:0xf bank_mask:0xf
	v_fmac_f32_dpp v138, v74, v204 row_shr:1 row_mask:0xf bank_mask:0xf
	v_fmac_f32_dpp v139, v75, v205 row_shr:1 row_mask:0xf bank_mask:0xf
	v_fmac_f32_dpp v132, v108, v186 row_shl:15 row_mask:0xf bank_mask:0xf
	v_fmac_f32_dpp v133, v109, v187 row_shl:15 row_mask:0xf bank_mask:0xf
	v_fmac_f32_dpp v134, v110, v188 row_shl:15 row_mask:0xf bank_mask:0xf
	v_fmac_f32_dpp v135, v111, v189 row_shl:15 row_mask:0xf bank_mask:0xf
	v_fmac_f32_dpp v136, v88, v202 row_shl:15 row_mask:0xf bank_mask:0xf
	v_fmac_f32_dpp v137, v89, v203 row_shl:15 row_mask:0xf bank_mask:0xf
	v_fmac_f32_dpp v138, v90, v204 row_shl:15 row_mask:0xf bank_mask:0xf
	v_fmac_f32_dpp v139, v91, v205 row_shl:15 row_mask:0xf bank_mask:0xf
	v_fmac_f32_dpp v132, v92, v182 row_shr:2 row_mask:0xf bank_mask:0xf
	v_fmac_f32_dpp v133, v93, v183 row_shr:2 row_mask:0xf bank_mask:0xf
	v_fmac_f32_dpp v134, v94, v184 row_shr:2 row_mask:0xf bank_mask:0xf
	v_fmac_f32_dpp v135, v95, v185 row_shr:2 row_mask:0xf bank_mask:0xf
	v_fmac_f32_dpp v136, v72, v198 row_shr:2 row_mask:0xf bank_mask:0xf
	v_fmac_f32_dpp v137, v73, v199 row_shr:2 row_mask:0xf bank_mask:0xf
	v_fmac_f32_dpp v138, v74, v200 row_shr:2 row_mask:0xf bank_mask:0xf
	v_fmac_f32_dpp v139, v75, v201 row_shr:2 row_mask:0xf bank_mask:0xf
	v_fmac_f32_dpp v132, v108, v182 row_shl:14 row_mask:0xf bank_mask:0xf
	v_fmac_f32_dpp v133, v109, v183 row_shl:14 row_mask:0xf bank_mask:0xf
	v_fmac_f32_dpp v134, v110, v184 row_shl:14 row_mask:0xf bank_mask:0xf
	v_fmac_f32_dpp v135, v111, v185 row_shl:14 row_mask:0xf bank_mask:0xf
	v_fmac_f32_dpp v136, v88, v198 row_shl:14 row_mask:0xf bank_mask:0xf
	v_fmac_f32_dpp v137, v89, v199 row_shl:14 row_mask:0xf bank_mask:0xf
	v_fmac_f32_dpp v138, v90, v200 row_shl:14 row_mask:0xf bank_mask:0xf
	v_fmac_f32_dpp v139, v91, v201 row_shl:14 row_mask:0xf bank_mask:0xf
	v_pk_mul_f32 v[140:141], v[132:133], v[132:133]
	v_pk_mul_f32 v[142:143], v[134:135], v[134:135]
	v_pk_fma_f32 v[140:141], v[140:141], s[98:99], v[244:245]
	v_pk_fma_f32 v[142:143], v[142:143], s[98:99], v[244:245]
	v_pk_mul_f32 v[140:141], v[132:133], v[140:141]
	v_pk_mul_f32 v[142:143], v[134:135], v[142:143]
	v_exp_f32_e32 v140, v140
	v_exp_f32_e32 v141, v141
	v_exp_f32_e32 v142, v142
	v_exp_f32_e32 v143, v143
	v_pk_add_f32 v[140:141], v[140:141], s[100:101]
	v_pk_add_f32 v[142:143], v[142:143], s[100:101]
	v_rcp_f32_e32 v140, v140
	v_rcp_f32_e32 v141, v141
	v_rcp_f32_e32 v142, v142
	v_rcp_f32_e32 v143, v143
	v_pk_mul_f32 v[140:141], v[132:133], v[140:141]
	v_pk_mul_f32 v[142:143], v[134:135], v[142:143]
	v_pk_mul_f32 v[140:141], v[140:141], v[136:137]
	v_pk_mul_f32 v[142:143], v[142:143], v[138:139]
	v_cvt_pk_bf16_f32 v130, v140, v141
	v_cvt_pk_bf16_f32 v131, v142, v143
	v_add_u32_e32 v144, 0x20, v248
	v_mad_u64_u32 v[144:145], vcc, v144, s4, v[242:243]
	global_store_dwordx4 v[144:145], v[128:131], off nt
	v_pk_fma_f32 v[132:133], v[84:85], v[158:159], v[146:147]
	v_pk_fma_f32 v[136:137], v[68:69], v[174:175], v[162:163]
	v_pk_fma_f32 v[134:135], v[86:87], v[160:161], v[148:149]
	v_pk_fma_f32 v[138:139], v[70:71], v[176:177], v[164:165]
	v_fmac_f32_dpp v132, v84, v154 row_shr:1 row_mask:0xf bank_mask:0xf
	v_fmac_f32_dpp v133, v85, v155 row_shr:1 row_mask:0xf bank_mask:0xf
; __device__ __forceinline__ unsigned pk2(float lo, float hi) { unsigned r; asm("v_cvt_pk_bf16_f32 %0, %1, %2" : "=v"(r) : "v"(lo), "v"(hi)); return r; }
;     __device__ __forceinline__ void operator()(const f32x4 (&acc)[2][2][4][2], const Unit& u, int wr, int wc, int fr, int fq) const {
;     ...
; #pragma unroll
;             for (int ai = 0; ai < 2; ++ai)
; #pragma unroll
;                 for (int m = 0; m < 4; ++m) { const int row = row0 + ai * HALF + m * 16;
;                     const f32x4 g0 = acc[ai][0][m][n], v0 = acc[ai][1][m][n];
;                     f32x4 gp = (f32x4){0.f, 0.f, 0.f, 0.f}, vp = gp;
;                     if (m > 0) { gp = acc[ai][0][m > 0 ? m - 1 : 0][n]; vp = acc[ai][1][m > 0 ? m - 1 : 0][n]; }
;                     f32x4 f;
; #pragma unroll
;                     for (int j = 0; j < 4; ++j) {
;                         const float g1 = dpp_shr1(dpp_ror1(gp[j]), g0[j]), g2 = dpp_shr2(dpp_ror2(gp[j]), g0[j]);
;                         const float v1 = dpp_shr1(dpp_ror1(vp[j]), v0[j]), v2 = dpp_shr2(dpp_ror2(vp[j]), v0[j]);
;                         const float cg_ = bg[j] + g2 * wg0[j] + g1 * wg1[j] + g0[j] * wg2[j];
;                         const float cv_ = bv[j] + v2 * wv0[j] + v1 * wv1[j] + v0[j] * wv2[j];
;                         f[j] = gelu_tanh(cg_) * cv_; }
;                     u32x2 w; w.x = pk2(f[0], f[1]); w.y = pk2(f[2], f[3]);
;                     if (n == 0) res0[ai * 4 + m] = w;
;                     else if (m > 0 || fr >= 2) { u32x4 w4; w4.x = res0[ai * 4 + m].x; w4.y = res0[ai * 4 + m].y; w4.z = w.x; w4.w = w.y; *(u32x4*)(F + (size_t)row * DFF + j0) = w4; }
;                     if (n == 1 && ((m == 0 && fr < 2) || (m == 3 && fr >= 14))) { const int slot = m == 0 ? fr : fr - 12;
;                         const f32x4 ga = acc[ai][0][m][0], va = acc[ai][1][m][0];
;                         bf16_t* bp = UPB + ((size_t)(row >> 6) * 4 + slot) * (2 * DFF) + col0;
;                         u32x4 wg_, wv_; wg_.x = pk2(ga[0], ga[1]); wg_.y = pk2(ga[2], ga[3]); wg_.z = pk2(g0[0], g0[1]); wg_.w = pk2(g0[2], g0[3]);
;                         wv_.x = pk2(va[0], va[1]); wv_.y = pk2(va[2], va[3]); wv_.z = pk2(v0[0], v0[1]); wv_.w = pk2(v0[2], v0[3]);
;                         *(u32x4*)bp = wg_; *(u32x4*)(bp + HALF) = wv_; } }
	v_fmac_f32_dpp v134, v86, v156 row_shr:1 row_mask:0xf bank_mask:0xf
	v_fmac_f32_dpp v135, v87, v157 row_shr:1 row_mask:0xf bank_mask:0xf
	v_fmac_f32_dpp v136, v68, v170 row_shr:1 row_mask:0xf bank_mask:0xf
	v_fmac_f32_dpp v137, v69, v171 row_shr:1 row_mask:0xf bank_mask:0xf
	v_fmac_f32_dpp v138, v70, v172 row_shr:1 row_mask:0xf bank_mask:0xf
	v_fmac_f32_dpp v139, v71, v173 row_shr:1 row_mask:0xf bank_mask:0xf
	v_fmac_f32_dpp v132, v100, v154 row_shl:15 row_mask:0xf bank_mask:0xf
	v_fmac_f32_dpp v133, v101, v155 row_shl:15 row_mask:0xf bank_mask:0xf
	v_fmac_f32_dpp v134, v102, v156 row_shl:15 row_mask:0xf bank_mask:0xf
	v_fmac_f32_dpp v135, v103, v157 row_shl:15 row_mask:0xf bank_mask:0xf
	v_fmac_f32_dpp v136, v80, v170 row_shl:15 row_mask:0xf bank_mask:0xf
	v_fmac_f32_dpp v137, v81, v171 row_shl:15 row_mask:0xf bank_mask:0xf
	v_fmac_f32_dpp v138, v82, v172 row_shl:15 row_mask:0xf bank_mask:0xf
	v_fmac_f32_dpp v139, v83, v173 row_shl:15 row_mask:0xf bank_mask:0xf
	v_fmac_f32_dpp v132, v84, v150 row_shr:2 row_mask:0xf bank_mask:0xf
	v_fmac_f32_dpp v133, v85, v151 row_shr:2 row_mask:0xf bank_mask:0xf
	v_fmac_f32_dpp v134, v86, v152 row_shr:2 row_mask:0xf bank_mask:0xf
	v_fmac_f32_dpp v135, v87, v153 row_shr:2 row_mask:0xf bank_mask:0xf
	v_fmac_f32_dpp v136, v68, v166 row_shr:2 row_mask:0xf bank_mask:0xf
	v_fmac_f32_dpp v137, v69, v167 row_shr:2 row_mask:0xf bank_mask:0xf
	v_fmac_f32_dpp v138, v70, v168 row_shr:2 row_mask:0xf bank_mask:0xf
	v_fmac_f32_dpp v139, v71, v169 row_shr:2 row_mask:0xf bank_mask:0xf
	v_fmac_f32_dpp v132, v100, v150 row_shl:14 row_mask:0xf bank_mask:0xf
	v_fmac_f32_dpp v133, v101, v151 row_shl:14 row_mask:0xf bank_mask:0xf
	v_fmac_f32_dpp v134, v102, v152 row_shl:14 row_mask:0xf bank_mask:0xf
	v_fmac_f32_dpp v135, v103, v153 row_shl:14 row_mask:0xf bank_mask:0xf
	v_fmac_f32_dpp v136, v80, v166 row_shl:14 row_mask:0xf bank_mask:0xf
	v_fmac_f32_dpp v137, v81, v167 row_shl:14 row_mask:0xf bank_mask:0xf
	v_fmac_f32_dpp v138, v82, v168 row_shl:14 row_mask:0xf bank_mask:0xf
	v_fmac_f32_dpp v139, v83, v169 row_shl:14 row_mask:0xf bank_mask:0xf
	v_pk_mul_f32 v[140:141], v[132:133], v[132:133]
	v_pk_mul_f32 v[142:143], v[134:135], v[134:135]
	v_pk_fma_f32 v[140:141], v[140:141], s[98:99], v[244:245]
	v_pk_fma_f32 v[142:143], v[142:143], s[98:99], v[244:245]
	v_pk_mul_f32 v[140:141], v[132:133], v[140:141]
	v_pk_mul_f32 v[142:143], v[134:135], v[142:143]
	v_exp_f32_e32 v140, v140
	v_exp_f32_e32 v141, v141
	v_exp_f32_e32 v142, v142
	v_exp_f32_e32 v143, v143
	v_pk_add_f32 v[140:141], v[140:141], s[100:101]
	v_pk_add_f32 v[142:143], v[142:143], s[100:101]
	v_rcp_f32_e32 v140, v140
	v_rcp_f32_e32 v141, v141
	v_rcp_f32_e32 v142, v142
	v_rcp_f32_e32 v143, v143
	v_pk_mul_f32 v[140:141], v[132:133], v[140:141]
	v_pk_mul_f32 v[142:143], v[134:135], v[142:143]
	v_pk_mul_f32 v[140:141], v[140:141], v[136:137]
	v_pk_mul_f32 v[142:143], v[142:143], v[138:139]
	v_cvt_pk_bf16_f32 v250, v140, v141
	v_cvt_pk_bf16_f32 v251, v142, v143
	v_pk_fma_f32 v[132:133], v[76:77], v[190:191], v[178:179]
	v_pk_fma_f32 v[136:137], v[64:65], v[206:207], v[194:195]
	v_pk_fma_f32 v[134:135], v[78:79], v[192:193], v[180:181]
	v_pk_fma_f32 v[138:139], v[66:67], v[208:209], v[196:197]
	v_fmac_f32_dpp v132, v76, v186 row_shr:1 row_mask:0xf bank_mask:0xf
	v_fmac_f32_dpp v133, v77, v187 row_shr:1 row_mask:0xf bank_mask:0xf
	v_fmac_f32_dpp v134, v78, v188 row_shr:1 row_mask:0xf bank_mask:0xf
	v_fmac_f32_dpp v135, v79, v189 row_shr:1 row_mask:0xf bank_mask:0xf
	v_fmac_f32_dpp v136, v64, v202 row_shr:1 row_mask:0xf bank_mask:0xf
	v_fmac_f32_dpp v137, v65, v203 row_shr:1 row_mask:0xf bank_mask:0xf
	v_fmac_f32_dpp v138, v66, v204 row_shr:1 row_mask:0xf bank_mask:0xf
	v_fmac_f32_dpp v139, v67, v205 row_shr:1 row_mask:0xf bank_mask:0xf
	v_fmac_f32_dpp v132, v92, v186 row_shl:15 row_mask:0xf bank_mask:0xf
	v_fmac_f32_dpp v133, v93, v187 row_shl:15 row_mask:0xf bank_mask:0xf
	v_fmac_f32_dpp v134, v94, v188 row_shl:15 row_mask:0xf bank_mask:0xf
	v_fmac_f32_dpp v135, v95, v189 row_shl:15 row_mask:0xf bank_mask:0xf
	v_fmac_f32_dpp v136, v72, v202 row_shl:15 row_mask:0xf bank_mask:0xf
	v_fmac_f32_dpp v137, v73, v203 row_shl:15 row_mask:0xf bank_mask:0xf
	v_fmac_f32_dpp v138, v74, v204 row_shl:15 row_mask:0xf bank_mask:0xf
	v_fmac_f32_dpp v139, v75, v205 row_shl:15 row_mask:0xf bank_mask:0xf
	v_fmac_f32_dpp v132, v76, v182 row_shr:2 row_mask:0xf bank_mask:0xf
	v_fmac_f32_dpp v133, v77, v183 row_shr:2 row_mask:0xf bank_mask:0xf
	v_fmac_f32_dpp v134, v78, v184 row_shr:2 row_mask:0xf bank_mask:0xf
	v_fmac_f32_dpp v135, v79, v185 row_shr:2 row_mask:0xf bank_mask:0xf
	v_fmac_f32_dpp v136, v64, v198 row_shr:2 row_mask:0xf bank_mask:0xf
	v_fmac_f32_dpp v137, v65, v199 row_shr:2 row_mask:0xf bank_mask:0xf
	v_fmac_f32_dpp v138, v66, v200 row_shr:2 row_mask:0xf bank_mask:0xf
	v_fmac_f32_dpp v139, v67, v201 row_shr:2 row_mask:0xf bank_mask:0xf
	v_fmac_f32_dpp v132, v92, v182 row_shl:14 row_mask:0xf bank_mask:0xf
	v_fmac_f32_dpp v133, v93, v183 row_shl:14 row_mask:0xf bank_mask:0xf
	v_fmac_f32_dpp v134, v94, v184 row_shl:14 row_mask:0xf bank_mask:0xf
	v_fmac_f32_dpp v135, v95, v185 row_shl:14 row_mask:0xf bank_mask:0xf
	v_fmac_f32_dpp v136, v72, v198 row_shl:14 row_mask:0xf bank_mask:0xf
	v_fmac_f32_dpp v137, v73, v199 row_shl:14 row_mask:0xf bank_mask:0xf
	v_fmac_f32_dpp v138, v74, v200 row_shl:14 row_mask:0xf bank_mask:0xf
	v_fmac_f32_dpp v139, v75, v201 row_shl:14 row_mask:0xf bank_mask:0xf
	v_pk_mul_f32 v[140:141], v[132:133], v[132:133]
	v_pk_mul_f32 v[142:143], v[134:135], v[134:135]
	v_pk_fma_f32 v[140:141], v[140:141], s[98:99], v[244:245]
	v_pk_fma_f32 v[142:143], v[142:143], s[98:99], v[244:245]
; __device__ __forceinline__ unsigned pk2(float lo, float hi) { unsigned r; asm("v_cvt_pk_bf16_f32 %0, %1, %2" : "=v"(r) : "v"(lo), "v"(hi)); return r; }
;     __device__ __forceinline__ void operator()(const f32x4 (&acc)[2][2][4][2], const Unit& u, int wr, int wc, int fr, int fq) const {
;     ...
; #pragma unroll
;             for (int ai = 0; ai < 2; ++ai)
; #pragma unroll
;                 for (int m = 0; m < 4; ++m) { const int row = row0 + ai * HALF + m * 16;
;                     const f32x4 g0 = acc[ai][0][m][n], v0 = acc[ai][1][m][n];
;                     f32x4 gp = (f32x4){0.f, 0.f, 0.f, 0.f}, vp = gp;
;                     if (m > 0) { gp = acc[ai][0][m > 0 ? m - 1 : 0][n]; vp = acc[ai][1][m > 0 ? m - 1 : 0][n]; }
;                     f32x4 f;
; #pragma unroll
;                     for (int j = 0; j < 4; ++j) {
;                         const float g1 = dpp_shr1(dpp_ror1(gp[j]), g0[j]), g2 = dpp_shr2(dpp_ror2(gp[j]), g0[j]);
;                         const float v1 = dpp_shr1(dpp_ror1(vp[j]), v0[j]), v2 = dpp_shr2(dpp_ror2(vp[j]), v0[j]);
;                         const float cg_ = bg[j] + g2 * wg0[j] + g1 * wg1[j] + g0[j] * wg2[j];
;                         const float cv_ = bv[j] + v2 * wv0[j] + v1 * wv1[j] + v0[j] * wv2[j];
;                         f[j] = gelu_tanh(cg_) * cv_; }
;                     u32x2 w; w.x = pk2(f[0], f[1]); w.y = pk2(f[2], f[3]);
;                     if (n == 0) res0[ai * 4 + m] = w;
;                     else if (m > 0 || fr >= 2) { u32x4 w4; w4.x = res0[ai * 4 + m].x; w4.y = res0[ai * 4 + m].y; w4.z = w.x; w4.w = w.y; *(u32x4*)(F + (size_t)row * DFF + j0) = w4; }
;                     if (n == 1 && ((m == 0 && fr < 2) || (m == 3 && fr >= 14))) { const int slot = m == 0 ? fr : fr - 12;
;                         const f32x4 ga = acc[ai][0][m][0], va = acc[ai][1][m][0];
;                         bf16_t* bp = UPB + ((size_t)(row >> 6) * 4 + slot) * (2 * DFF) + col0;
;                         u32x4 wg_, wv_; wg_.x = pk2(ga[0], ga[1]); wg_.y = pk2(ga[2], ga[3]); wg_.z = pk2(g0[0], g0[1]); wg_.w = pk2(g0[2], g0[3]);
;                         wv_.x = pk2(va[0], va[1]); wv_.y = pk2(va[2], va[3]); wv_.z = pk2(v0[0], v0[1]); wv_.w = pk2(v0[2], v0[3]);
;                         *(u32x4*)bp = wg_; *(u32x4*)(bp + HALF) = wv_; } }
	v_pk_mul_f32 v[140:141], v[132:133], v[140:141]
	v_pk_mul_f32 v[142:143], v[134:135], v[142:143]
	v_exp_f32_e32 v140, v140
	v_exp_f32_e32 v141, v141
	v_exp_f32_e32 v142, v142
	v_exp_f32_e32 v143, v143
	v_pk_add_f32 v[140:141], v[140:141], s[100:101]
	v_pk_add_f32 v[142:143], v[142:143], s[100:101]
	v_rcp_f32_e32 v140, v140
	v_rcp_f32_e32 v141, v141
	v_rcp_f32_e32 v142, v142
	v_rcp_f32_e32 v143, v143
	v_pk_mul_f32 v[140:141], v[132:133], v[140:141]
	v_pk_mul_f32 v[142:143], v[134:135], v[142:143]
	v_pk_mul_f32 v[140:141], v[140:141], v[136:137]
	v_pk_mul_f32 v[142:143], v[142:143], v[138:139]
	v_cvt_pk_bf16_f32 v252, v140, v141
	v_cvt_pk_bf16_f32 v253, v142, v143
	v_add_u32_e32 v144, 0x30, v248
	v_mad_u64_u32 v[144:145], vcc, v144, s4, v[242:243]
	global_store_dwordx4 v[144:145], v[250:253], off nt
	v_pk_fma_f32 v[132:133], v[60:61], v[158:159], v[146:147]
	v_pk_fma_f32 v[136:137], v[48:49], v[174:175], v[162:163]
	v_pk_fma_f32 v[134:135], v[62:63], v[160:161], v[148:149]
	v_pk_fma_f32 v[138:139], v[50:51], v[176:177], v[164:165]
	v_fmac_f32_dpp v132, v60, v154 row_shr:1 row_mask:0xf bank_mask:0xf
	v_fmac_f32_dpp v133, v61, v155 row_shr:1 row_mask:0xf bank_mask:0xf
	v_fmac_f32_dpp v134, v62, v156 row_shr:1 row_mask:0xf bank_mask:0xf
	v_fmac_f32_dpp v135, v63, v157 row_shr:1 row_mask:0xf bank_mask:0xf
	v_fmac_f32_dpp v136, v48, v170 row_shr:1 row_mask:0xf bank_mask:0xf
	v_fmac_f32_dpp v137, v49, v171 row_shr:1 row_mask:0xf bank_mask:0xf
	v_fmac_f32_dpp v138, v50, v172 row_shr:1 row_mask:0xf bank_mask:0xf
	v_fmac_f32_dpp v139, v51, v173 row_shr:1 row_mask:0xf bank_mask:0xf
	v_fmac_f32_dpp v132, v60, v150 row_shr:2 row_mask:0xf bank_mask:0xf
	v_fmac_f32_dpp v133, v61, v151 row_shr:2 row_mask:0xf bank_mask:0xf
	v_fmac_f32_dpp v134, v62, v152 row_shr:2 row_mask:0xf bank_mask:0xf
	v_fmac_f32_dpp v135, v63, v153 row_shr:2 row_mask:0xf bank_mask:0xf
	v_fmac_f32_dpp v136, v48, v166 row_shr:2 row_mask:0xf bank_mask:0xf
	v_fmac_f32_dpp v137, v49, v167 row_shr:2 row_mask:0xf bank_mask:0xf
	v_fmac_f32_dpp v138, v50, v168 row_shr:2 row_mask:0xf bank_mask:0xf
	v_fmac_f32_dpp v139, v51, v169 row_shr:2 row_mask:0xf bank_mask:0xf
	v_pk_mul_f32 v[140:141], v[132:133], v[132:133]
	v_pk_mul_f32 v[142:143], v[134:135], v[134:135]
	v_pk_fma_f32 v[140:141], v[140:141], s[98:99], v[244:245]
	v_pk_fma_f32 v[142:143], v[142:143], s[98:99], v[244:245]
	v_pk_mul_f32 v[140:141], v[132:133], v[140:141]
	v_pk_mul_f32 v[142:143], v[134:135], v[142:143]
	v_exp_f32_e32 v140, v140
	v_exp_f32_e32 v141, v141
	v_exp_f32_e32 v142, v142
	v_exp_f32_e32 v143, v143
	v_pk_add_f32 v[140:141], v[140:141], s[100:101]
	v_pk_add_f32 v[142:143], v[142:143], s[100:101]
	v_rcp_f32_e32 v140, v140
	v_rcp_f32_e32 v141, v141
	v_rcp_f32_e32 v142, v142
	v_rcp_f32_e32 v143, v143
	v_pk_mul_f32 v[140:141], v[132:133], v[140:141]
	v_pk_mul_f32 v[142:143], v[134:135], v[142:143]
	v_pk_mul_f32 v[140:141], v[140:141], v[136:137]
	v_pk_mul_f32 v[142:143], v[142:143], v[138:139]
	v_cvt_pk_bf16_f32 v128, v140, v141
	v_cvt_pk_bf16_f32 v129, v142, v143
	v_pk_fma_f32 v[132:133], v[56:57], v[190:191], v[178:179]
	v_pk_fma_f32 v[136:137], v[40:41], v[206:207], v[194:195]
	v_pk_fma_f32 v[134:135], v[58:59], v[192:193], v[180:181]
	v_pk_fma_f32 v[138:139], v[42:43], v[208:209], v[196:197]
	v_fmac_f32_dpp v132, v56, v186 row_shr:1 row_mask:0xf bank_mask:0xf
	v_fmac_f32_dpp v133, v57, v187 row_shr:1 row_mask:0xf bank_mask:0xf
	v_fmac_f32_dpp v134, v58, v188 row_shr:1 row_mask:0xf bank_mask:0xf
	v_fmac_f32_dpp v135, v59, v189 row_shr:1 row_mask:0xf bank_mask:0xf
	v_fmac_f32_dpp v136, v40, v202 row_shr:1 row_mask:0xf bank_mask:0xf
	v_fmac_f32_dpp v137, v41, v203 row_shr:1 row_mask:0xf bank_mask:0xf
	v_fmac_f32_dpp v138, v42, v204 row_shr:1 row_mask:0xf bank_mask:0xf
	v_fmac_f32_dpp v139, v43, v205 row_shr:1 row_mask:0xf bank_mask:0xf
	v_fmac_f32_dpp v132, v56, v182 row_shr:2 row_mask:0xf bank_mask:0xf
	v_fmac_f32_dpp v133, v57, v183 row_shr:2 row_mask:0xf bank_mask:0xf
	v_fmac_f32_dpp v134, v58, v184 row_shr:2 row_mask:0xf bank_mask:0xf
	v_fmac_f32_dpp v135, v59, v185 row_shr:2 row_mask:0xf bank_mask:0xf
	v_fmac_f32_dpp v136, v40, v198 row_shr:2 row_mask:0xf bank_mask:0xf
	v_fmac_f32_dpp v137, v41, v199 row_shr:2 row_mask:0xf bank_mask:0xf
	v_fmac_f32_dpp v138, v42, v200 row_shr:2 row_mask:0xf bank_mask:0xf
	v_fmac_f32_dpp v139, v43, v201 row_shr:2 row_mask:0xf bank_mask:0xf
	v_pk_mul_f32 v[140:141], v[132:133], v[132:133]
	v_pk_mul_f32 v[142:143], v[134:135], v[134:135]
	v_pk_fma_f32 v[140:141], v[140:141], s[98:99], v[244:245]
	v_pk_fma_f32 v[142:143], v[142:143], s[98:99], v[244:245]
	v_pk_mul_f32 v[140:141], v[132:133], v[140:141]
	v_pk_mul_f32 v[142:143], v[134:135], v[142:143]
	v_exp_f32_e32 v140, v140
	v_exp_f32_e32 v141, v141
	v_exp_f32_e32 v142, v142
	v_exp_f32_e32 v143, v143
	v_pk_add_f32 v[140:141], v[140:141], s[100:101]
	v_pk_add_f32 v[142:143], v[142:143], s[100:101]
	v_rcp_f32_e32 v140, v140
	v_rcp_f32_e32 v141, v141
	v_rcp_f32_e32 v142, v142
	v_rcp_f32_e32 v143, v143
	v_pk_mul_f32 v[140:141], v[132:133], v[140:141]
	v_pk_mul_f32 v[142:143], v[134:135], v[142:143]
	v_pk_mul_f32 v[140:141], v[140:141], v[136:137]
	v_pk_mul_f32 v[142:143], v[142:143], v[138:139]
	v_cvt_pk_bf16_f32 v130, v140, v141
	v_cvt_pk_bf16_f32 v131, v142, v143
	s_and_saveexec_b64 s[42:43], s[8:9]
	v_add_u32_e32 v144, 0x80, v248
	v_mad_u64_u32 v[144:145], vcc, v144, s4, v[242:243]
	global_store_dwordx4 v[144:145], v[128:131], off nt
	s_or_b64 exec, exec, s[42:43]
	s_nop 4
	v_pk_fma_f32 v[132:133], v[52:53], v[158:159], v[146:147]
	v_pk_fma_f32 v[136:137], v[32:33], v[174:175], v[162:163]
	v_pk_fma_f32 v[134:135], v[54:55], v[160:161], v[148:149]
; __device__ __forceinline__ unsigned pk2(float lo, float hi) { unsigned r; asm("v_cvt_pk_bf16_f32 %0, %1, %2" : "=v"(r) : "v"(lo), "v"(hi)); return r; }
;     __device__ __forceinline__ void operator()(const f32x4 (&acc)[2][2][4][2], const Unit& u, int wr, int wc, int fr, int fq) const {
;     ...
; #pragma unroll
;             for (int ai = 0; ai < 2; ++ai)
; #pragma unroll
;                 for (int m = 0; m < 4; ++m) { const int row = row0 + ai * HALF + m * 16;
;                     const f32x4 g0 = acc[ai][0][m][n], v0 = acc[ai][1][m][n];
;                     f32x4 gp = (f32x4){0.f, 0.f, 0.f, 0.f}, vp = gp;
;                     if (m > 0) { gp = acc[ai][0][m > 0 ? m - 1 : 0][n]; vp = acc[ai][1][m > 0 ? m - 1 : 0][n]; }
;                     f32x4 f;
; #pragma unroll
;                     for (int j = 0; j < 4; ++j) {
;                         const float g1 = dpp_shr1(dpp_ror1(gp[j]), g0[j]), g2 = dpp_shr2(dpp_ror2(gp[j]), g0[j]);
;                         const float v1 = dpp_shr1(dpp_ror1(vp[j]), v0[j]), v2 = dpp_shr2(dpp_ror2(vp[j]), v0[j]);
;                         const float cg_ = bg[j] + g2 * wg0[j] + g1 * wg1[j] + g0[j] * wg2[j];
;                         const float cv_ = bv[j] + v2 * wv0[j] + v1 * wv1[j] + v0[j] * wv2[j];
;                         f[j] = gelu_tanh(cg_) * cv_; }
;                     u32x2 w; w.x = pk2(f[0], f[1]); w.y = pk2(f[2], f[3]);
;                     if (n == 0) res0[ai * 4 + m] = w;
;                     else if (m > 0 || fr >= 2) { u32x4 w4; w4.x = res0[ai * 4 + m].x; w4.y = res0[ai * 4 + m].y; w4.z = w.x; w4.w = w.y; *(u32x4*)(F + (size_t)row * DFF + j0) = w4; }
;                     if (n == 1 && ((m == 0 && fr < 2) || (m == 3 && fr >= 14))) { const int slot = m == 0 ? fr : fr - 12;
;                         const f32x4 ga = acc[ai][0][m][0], va = acc[ai][1][m][0];
;                         bf16_t* bp = UPB + ((size_t)(row >> 6) * 4 + slot) * (2 * DFF) + col0;
;                         u32x4 wg_, wv_; wg_.x = pk2(ga[0], ga[1]); wg_.y = pk2(ga[2], ga[3]); wg_.z = pk2(g0[0], g0[1]); wg_.w = pk2(g0[2], g0[3]);
;                         wv_.x = pk2(va[0], va[1]); wv_.y = pk2(va[2], va[3]); wv_.z = pk2(v0[0], v0[1]); wv_.w = pk2(v0[2], v0[3]);
;                         *(u32x4*)bp = wg_; *(u32x4*)(bp + HALF) = wv_; } }
	v_pk_fma_f32 v[138:139], v[34:35], v[176:177], v[164:165]
	v_fmac_f32_dpp v132, v52, v154 row_shr:1 row_mask:0xf bank_mask:0xf
	v_fmac_f32_dpp v133, v53, v155 row_shr:1 row_mask:0xf bank_mask:0xf
	v_fmac_f32_dpp v134, v54, v156 row_shr:1 row_mask:0xf bank_mask:0xf
	v_fmac_f32_dpp v135, v55, v157 row_shr:1 row_mask:0xf bank_mask:0xf
	v_fmac_f32_dpp v136, v32, v170 row_shr:1 row_mask:0xf bank_mask:0xf
	v_fmac_f32_dpp v137, v33, v171 row_shr:1 row_mask:0xf bank_mask:0xf
	v_fmac_f32_dpp v138, v34, v172 row_shr:1 row_mask:0xf bank_mask:0xf
	v_fmac_f32_dpp v139, v35, v173 row_shr:1 row_mask:0xf bank_mask:0xf
	v_fmac_f32_dpp v132, v60, v154 row_shl:15 row_mask:0xf bank_mask:0xf
	v_fmac_f32_dpp v133, v61, v155 row_shl:15 row_mask:0xf bank_mask:0xf
	v_fmac_f32_dpp v134, v62, v156 row_shl:15 row_mask:0xf bank_mask:0xf
	v_fmac_f32_dpp v135, v63, v157 row_shl:15 row_mask:0xf bank_mask:0xf
	v_fmac_f32_dpp v136, v48, v170 row_shl:15 row_mask:0xf bank_mask:0xf
	v_fmac_f32_dpp v137, v49, v171 row_shl:15 row_mask:0xf bank_mask:0xf
	v_fmac_f32_dpp v138, v50, v172 row_shl:15 row_mask:0xf bank_mask:0xf
	v_fmac_f32_dpp v139, v51, v173 row_shl:15 row_mask:0xf bank_mask:0xf
	v_fmac_f32_dpp v132, v52, v150 row_shr:2 row_mask:0xf bank_mask:0xf
	v_fmac_f32_dpp v133, v53, v151 row_shr:2 row_mask:0xf bank_mask:0xf
	v_fmac_f32_dpp v134, v54, v152 row_shr:2 row_mask:0xf bank_mask:0xf
	v_fmac_f32_dpp v135, v55, v153 row_shr:2 row_mask:0xf bank_mask:0xf
	v_fmac_f32_dpp v136, v32, v166 row_shr:2 row_mask:0xf bank_mask:0xf
	v_fmac_f32_dpp v137, v33, v167 row_shr:2 row_mask:0xf bank_mask:0xf
	v_fmac_f32_dpp v138, v34, v168 row_shr:2 row_mask:0xf bank_mask:0xf
	v_fmac_f32_dpp v139, v35, v169 row_shr:2 row_mask:0xf bank_mask:0xf
	v_fmac_f32_dpp v132, v60, v150 row_shl:14 row_mask:0xf bank_mask:0xf
	v_fmac_f32_dpp v133, v61, v151 row_shl:14 row_mask:0xf bank_mask:0xf
	v_fmac_f32_dpp v134, v62, v152 row_shl:14 row_mask:0xf bank_mask:0xf
	v_fmac_f32_dpp v135, v63, v153 row_shl:14 row_mask:0xf bank_mask:0xf
	v_fmac_f32_dpp v136, v48, v166 row_shl:14 row_mask:0xf bank_mask:0xf
	v_fmac_f32_dpp v137, v49, v167 row_shl:14 row_mask:0xf bank_mask:0xf
	v_fmac_f32_dpp v138, v50, v168 row_shl:14 row_mask:0xf bank_mask:0xf
	v_fmac_f32_dpp v139, v51, v169 row_shl:14 row_mask:0xf bank_mask:0xf
	v_pk_mul_f32 v[140:141], v[132:133], v[132:133]
	v_pk_mul_f32 v[142:143], v[134:135], v[134:135]
	v_pk_fma_f32 v[140:141], v[140:141], s[98:99], v[244:245]
	v_pk_fma_f32 v[142:143], v[142:143], s[98:99], v[244:245]
	v_pk_mul_f32 v[140:141], v[132:133], v[140:141]
	v_pk_mul_f32 v[142:143], v[134:135], v[142:143]
	v_exp_f32_e32 v140, v140
	v_exp_f32_e32 v141, v141
	v_exp_f32_e32 v142, v142
	v_exp_f32_e32 v143, v143
	v_pk_add_f32 v[140:141], v[140:141], s[100:101]
	v_pk_add_f32 v[142:143], v[142:143], s[100:101]
	v_rcp_f32_e32 v140, v140
	v_rcp_f32_e32 v141, v141
	v_rcp_f32_e32 v142, v142
	v_rcp_f32_e32 v143, v143
	v_pk_mul_f32 v[140:141], v[132:133], v[140:141]
	v_pk_mul_f32 v[142:143], v[134:135], v[142:143]
	v_pk_mul_f32 v[140:141], v[140:141], v[136:137]
	v_pk_mul_f32 v[142:143], v[142:143], v[138:139]
	v_cvt_pk_bf16_f32 v250, v140, v141
	v_cvt_pk_bf16_f32 v251, v142, v143
	v_pk_fma_f32 v[132:133], v[44:45], v[190:191], v[178:179]
	v_pk_fma_f32 v[136:137], v[24:25], v[206:207], v[194:195]
	v_pk_fma_f32 v[134:135], v[46:47], v[192:193], v[180:181]
	v_pk_fma_f32 v[138:139], v[26:27], v[208:209], v[196:197]
	v_fmac_f32_dpp v132, v44, v186 row_shr:1 row_mask:0xf bank_mask:0xf
	v_fmac_f32_dpp v133, v45, v187 row_shr:1 row_mask:0xf bank_mask:0xf
	v_fmac_f32_dpp v134, v46, v188 row_shr:1 row_mask:0xf bank_mask:0xf
	v_fmac_f32_dpp v135, v47, v189 row_shr:1 row_mask:0xf bank_mask:0xf
	v_fmac_f32_dpp v136, v24, v202 row_shr:1 row_mask:0xf bank_mask:0xf
	v_fmac_f32_dpp v137, v25, v203 row_shr:1 row_mask:0xf bank_mask:0xf
	v_fmac_f32_dpp v138, v26, v204 row_shr:1 row_mask:0xf bank_mask:0xf
	v_fmac_f32_dpp v139, v27, v205 row_shr:1 row_mask:0xf bank_mask:0xf
	v_fmac_f32_dpp v132, v56, v186 row_shl:15 row_mask:0xf bank_mask:0xf
	v_fmac_f32_dpp v133, v57, v187 row_shl:15 row_mask:0xf bank_mask:0xf
	v_fmac_f32_dpp v134, v58, v188 row_shl:15 row_mask:0xf bank_mask:0xf
	v_fmac_f32_dpp v135, v59, v189 row_shl:15 row_mask:0xf bank_mask:0xf
	v_fmac_f32_dpp v136, v40, v202 row_shl:15 row_mask:0xf bank_mask:0xf
	v_fmac_f32_dpp v137, v41, v203 row_shl:15 row_mask:0xf bank_mask:0xf
	v_fmac_f32_dpp v138, v42, v204 row_shl:15 row_mask:0xf bank_mask:0xf
	v_fmac_f32_dpp v139, v43, v205 row_shl:15 row_mask:0xf bank_mask:0xf
	v_fmac_f32_dpp v132, v44, v182 row_shr:2 row_mask:0xf bank_mask:0xf
	v_fmac_f32_dpp v133, v45, v183 row_shr:2 row_mask:0xf bank_mask:0xf
	v_fmac_f32_dpp v134, v46, v184 row_shr:2 row_mask:0xf bank_mask:0xf
	v_fmac_f32_dpp v135, v47, v185 row_shr:2 row_mask:0xf bank_mask:0xf
	v_fmac_f32_dpp v136, v24, v198 row_shr:2 row_mask:0xf bank_mask:0xf
	v_fmac_f32_dpp v137, v25, v199 row_shr:2 row_mask:0xf bank_mask:0xf
	v_fmac_f32_dpp v138, v26, v200 row_shr:2 row_mask:0xf bank_mask:0xf
	v_fmac_f32_dpp v139, v27, v201 row_shr:2 row_mask:0xf bank_mask:0xf
	v_fmac_f32_dpp v132, v56, v182 row_shl:14 row_mask:0xf bank_mask:0xf
	v_fmac_f32_dpp v133, v57, v183 row_shl:14 row_mask:0xf bank_mask:0xf
	v_fmac_f32_dpp v134, v58, v184 row_shl:14 row_mask:0xf bank_mask:0xf
	v_fmac_f32_dpp v135, v59, v185 row_shl:14 row_mask:0xf bank_mask:0xf
	v_fmac_f32_dpp v136, v40, v198 row_shl:14 row_mask:0xf bank_mask:0xf
	v_fmac_f32_dpp v137, v41, v199 row_shl:14 row_mask:0xf bank_mask:0xf
	v_fmac_f32_dpp v138, v42, v200 row_shl:14 row_mask:0xf bank_mask:0xf
	v_fmac_f32_dpp v139, v43, v201 row_shl:14 row_mask:0xf bank_mask:0xf
; __device__ __forceinline__ unsigned pk2(float lo, float hi) { unsigned r; asm("v_cvt_pk_bf16_f32 %0, %1, %2" : "=v"(r) : "v"(lo), "v"(hi)); return r; }
;     __device__ __forceinline__ void operator()(const f32x4 (&acc)[2][2][4][2], const Unit& u, int wr, int wc, int fr, int fq) const {
;     ...
; #pragma unroll
;             for (int ai = 0; ai < 2; ++ai)
; #pragma unroll
;                 for (int m = 0; m < 4; ++m) { const int row = row0 + ai * HALF + m * 16;
;                     const f32x4 g0 = acc[ai][0][m][n], v0 = acc[ai][1][m][n];
;                     f32x4 gp = (f32x4){0.f, 0.f, 0.f, 0.f}, vp = gp;
;                     if (m > 0) { gp = acc[ai][0][m > 0 ? m - 1 : 0][n]; vp = acc[ai][1][m > 0 ? m - 1 : 0][n]; }
;                     f32x4 f;
; #pragma unroll
;                     for (int j = 0; j < 4; ++j) {
;                         const float g1 = dpp_shr1(dpp_ror1(gp[j]), g0[j]), g2 = dpp_shr2(dpp_ror2(gp[j]), g0[j]);
;                         const float v1 = dpp_shr1(dpp_ror1(vp[j]), v0[j]), v2 = dpp_shr2(dpp_ror2(vp[j]), v0[j]);
;                         const float cg_ = bg[j] + g2 * wg0[j] + g1 * wg1[j] + g0[j] * wg2[j];
;                         const float cv_ = bv[j] + v2 * wv0[j] + v1 * wv1[j] + v0[j] * wv2[j];
;                         f[j] = gelu_tanh(cg_) * cv_; }
;                     u32x2 w; w.x = pk2(f[0], f[1]); w.y = pk2(f[2], f[3]);
;                     if (n == 0) res0[ai * 4 + m] = w;
;                     else if (m > 0 || fr >= 2) { u32x4 w4; w4.x = res0[ai * 4 + m].x; w4.y = res0[ai * 4 + m].y; w4.z = w.x; w4.w = w.y; *(u32x4*)(F + (size_t)row * DFF + j0) = w4; }
;                     if (n == 1 && ((m == 0 && fr < 2) || (m == 3 && fr >= 14))) { const int slot = m == 0 ? fr : fr - 12;
;                         const f32x4 ga = acc[ai][0][m][0], va = acc[ai][1][m][0];
;                         bf16_t* bp = UPB + ((size_t)(row >> 6) * 4 + slot) * (2 * DFF) + col0;
;                         u32x4 wg_, wv_; wg_.x = pk2(ga[0], ga[1]); wg_.y = pk2(ga[2], ga[3]); wg_.z = pk2(g0[0], g0[1]); wg_.w = pk2(g0[2], g0[3]);
;                         wv_.x = pk2(va[0], va[1]); wv_.y = pk2(va[2], va[3]); wv_.z = pk2(v0[0], v0[1]); wv_.w = pk2(v0[2], v0[3]);
;                         *(u32x4*)bp = wg_; *(u32x4*)(bp + HALF) = wv_; } }
	v_pk_mul_f32 v[140:141], v[132:133], v[132:133]
	v_pk_mul_f32 v[142:143], v[134:135], v[134:135]
	v_pk_fma_f32 v[140:141], v[140:141], s[98:99], v[244:245]
	v_pk_fma_f32 v[142:143], v[142:143], s[98:99], v[244:245]
	v_pk_mul_f32 v[140:141], v[132:133], v[140:141]
	v_pk_mul_f32 v[142:143], v[134:135], v[142:143]
	v_exp_f32_e32 v140, v140
	v_exp_f32_e32 v141, v141
	v_exp_f32_e32 v142, v142
	v_exp_f32_e32 v143, v143
	v_pk_add_f32 v[140:141], v[140:141], s[100:101]
	v_pk_add_f32 v[142:143], v[142:143], s[100:101]
	v_rcp_f32_e32 v140, v140
	v_rcp_f32_e32 v141, v141
	v_rcp_f32_e32 v142, v142
	v_rcp_f32_e32 v143, v143
	v_pk_mul_f32 v[140:141], v[132:133], v[140:141]
	v_pk_mul_f32 v[142:143], v[134:135], v[142:143]
	v_pk_mul_f32 v[140:141], v[140:141], v[136:137]
	v_pk_mul_f32 v[142:143], v[142:143], v[138:139]
	v_cvt_pk_bf16_f32 v252, v140, v141
	v_cvt_pk_bf16_f32 v253, v142, v143
	v_add_u32_e32 v144, 0x90, v248
	v_mad_u64_u32 v[144:145], vcc, v144, s4, v[242:243]
	global_store_dwordx4 v[144:145], v[250:253], off nt
	v_pk_fma_f32 v[132:133], v[36:37], v[158:159], v[146:147]
	v_pk_fma_f32 v[136:137], v[16:17], v[174:175], v[162:163]
	v_pk_fma_f32 v[134:135], v[38:39], v[160:161], v[148:149]
	v_pk_fma_f32 v[138:139], v[18:19], v[176:177], v[164:165]
	v_fmac_f32_dpp v132, v36, v154 row_shr:1 row_mask:0xf bank_mask:0xf
	v_fmac_f32_dpp v133, v37, v155 row_shr:1 row_mask:0xf bank_mask:0xf
	v_fmac_f32_dpp v134, v38, v156 row_shr:1 row_mask:0xf bank_mask:0xf
	v_fmac_f32_dpp v135, v39, v157 row_shr:1 row_mask:0xf bank_mask:0xf
	v_fmac_f32_dpp v136, v16, v170 row_shr:1 row_mask:0xf bank_mask:0xf
	v_fmac_f32_dpp v137, v17, v171 row_shr:1 row_mask:0xf bank_mask:0xf
	v_fmac_f32_dpp v138, v18, v172 row_shr:1 row_mask:0xf bank_mask:0xf
	v_fmac_f32_dpp v139, v19, v173 row_shr:1 row_mask:0xf bank_mask:0xf
	v_fmac_f32_dpp v132, v52, v154 row_shl:15 row_mask:0xf bank_mask:0xf
	v_fmac_f32_dpp v133, v53, v155 row_shl:15 row_mask:0xf bank_mask:0xf
	v_fmac_f32_dpp v134, v54, v156 row_shl:15 row_mask:0xf bank_mask:0xf
	v_fmac_f32_dpp v135, v55, v157 row_shl:15 row_mask:0xf bank_mask:0xf
	v_fmac_f32_dpp v136, v32, v170 row_shl:15 row_mask:0xf bank_mask:0xf
	v_fmac_f32_dpp v137, v33, v171 row_shl:15 row_mask:0xf bank_mask:0xf
	v_fmac_f32_dpp v138, v34, v172 row_shl:15 row_mask:0xf bank_mask:0xf
	v_fmac_f32_dpp v139, v35, v173 row_shl:15 row_mask:0xf bank_mask:0xf
	v_fmac_f32_dpp v132, v36, v150 row_shr:2 row_mask:0xf bank_mask:0xf
	v_fmac_f32_dpp v133, v37, v151 row_shr:2 row_mask:0xf bank_mask:0xf
	v_fmac_f32_dpp v134, v38, v152 row_shr:2 row_mask:0xf bank_mask:0xf
	v_fmac_f32_dpp v135, v39, v153 row_shr:2 row_mask:0xf bank_mask:0xf
	v_fmac_f32_dpp v136, v16, v166 row_shr:2 row_mask:0xf bank_mask:0xf
	v_fmac_f32_dpp v137, v17, v167 row_shr:2 row_mask:0xf bank_mask:0xf
	v_fmac_f32_dpp v138, v18, v168 row_shr:2 row_mask:0xf bank_mask:0xf
	v_fmac_f32_dpp v139, v19, v169 row_shr:2 row_mask:0xf bank_mask:0xf
	v_fmac_f32_dpp v132, v52, v150 row_shl:14 row_mask:0xf bank_mask:0xf
	v_fmac_f32_dpp v133, v53, v151 row_shl:14 row_mask:0xf bank_mask:0xf
	v_fmac_f32_dpp v134, v54, v152 row_shl:14 row_mask:0xf bank_mask:0xf
	v_fmac_f32_dpp v135, v55, v153 row_shl:14 row_mask:0xf bank_mask:0xf
	v_fmac_f32_dpp v136, v32, v166 row_shl:14 row_mask:0xf bank_mask:0xf
	v_fmac_f32_dpp v137, v33, v167 row_shl:14 row_mask:0xf bank_mask:0xf
	v_fmac_f32_dpp v138, v34, v168 row_shl:14 row_mask:0xf bank_mask:0xf
	v_fmac_f32_dpp v139, v35, v169 row_shl:14 row_mask:0xf bank_mask:0xf
	v_pk_mul_f32 v[140:141], v[132:133], v[132:133]
	v_pk_mul_f32 v[142:143], v[134:135], v[134:135]
	v_pk_fma_f32 v[140:141], v[140:141], s[98:99], v[244:245]
	v_pk_fma_f32 v[142:143], v[142:143], s[98:99], v[244:245]
	v_pk_mul_f32 v[140:141], v[132:133], v[140:141]
	v_pk_mul_f32 v[142:143], v[134:135], v[142:143]
	v_exp_f32_e32 v140, v140
	v_exp_f32_e32 v141, v141
	v_exp_f32_e32 v142, v142
	v_exp_f32_e32 v143, v143
	v_pk_add_f32 v[140:141], v[140:141], s[100:101]
	v_pk_add_f32 v[142:143], v[142:143], s[100:101]
	v_rcp_f32_e32 v140, v140
	v_rcp_f32_e32 v141, v141
	v_rcp_f32_e32 v142, v142
	v_rcp_f32_e32 v143, v143
	v_pk_mul_f32 v[140:141], v[132:133], v[140:141]
	v_pk_mul_f32 v[142:143], v[134:135], v[142:143]
	v_pk_mul_f32 v[140:141], v[140:141], v[136:137]
	v_pk_mul_f32 v[142:143], v[142:143], v[138:139]
	v_cvt_pk_bf16_f32 v128, v140, v141
	v_cvt_pk_bf16_f32 v129, v142, v143
	v_pk_fma_f32 v[132:133], v[28:29], v[190:191], v[178:179]
	v_pk_fma_f32 v[136:137], v[8:9], v[206:207], v[194:195]
	v_pk_fma_f32 v[134:135], v[30:31], v[192:193], v[180:181]
	v_pk_fma_f32 v[138:139], v[10:11], v[208:209], v[196:197]
	v_fmac_f32_dpp v132, v28, v186 row_shr:1 row_mask:0xf bank_mask:0xf
	v_fmac_f32_dpp v133, v29, v187 row_shr:1 row_mask:0xf bank_mask:0xf
	v_fmac_f32_dpp v134, v30, v188 row_shr:1 row_mask:0xf bank_mask:0xf
	v_fmac_f32_dpp v135, v31, v189 row_shr:1 row_mask:0xf bank_mask:0xf
	v_fmac_f32_dpp v136, v8, v202 row_shr:1 row_mask:0xf bank_mask:0xf
	v_fmac_f32_dpp v137, v9, v203 row_shr:1 row_mask:0xf bank_mask:0xf
	v_fmac_f32_dpp v138, v10, v204 row_shr:1 row_mask:0xf bank_mask:0xf
	v_fmac_f32_dpp v139, v11, v205 row_shr:1 row_mask:0xf bank_mask:0xf
	v_fmac_f32_dpp v132, v44, v186 row_shl:15 row_mask:0xf bank_mask:0xf
	v_fmac_f32_dpp v133, v45, v187 row_shl:15 row_mask:0xf bank_mask:0xf
	v_fmac_f32_dpp v134, v46, v188 row_shl:15 row_mask:0xf bank_mask:0xf
	v_fmac_f32_dpp v135, v47, v189 row_shl:15 row_mask:0xf bank_mask:0xf
	v_fmac_f32_dpp v136, v24, v202 row_shl:15 row_mask:0xf bank_mask:0xf
	v_fmac_f32_dpp v137, v25, v203 row_shl:15 row_mask:0xf bank_mask:0xf
	v_fmac_f32_dpp v138, v26, v204 row_shl:15 row_mask:0xf bank_mask:0xf
; __device__ __forceinline__ unsigned pk2(float lo, float hi) { unsigned r; asm("v_cvt_pk_bf16_f32 %0, %1, %2" : "=v"(r) : "v"(lo), "v"(hi)); return r; }
;     __device__ __forceinline__ void operator()(const f32x4 (&acc)[2][2][4][2], const Unit& u, int wr, int wc, int fr, int fq) const {
;     ...
; #pragma unroll
;             for (int ai = 0; ai < 2; ++ai)
; #pragma unroll
;                 for (int m = 0; m < 4; ++m) { const int row = row0 + ai * HALF + m * 16;
;                     const f32x4 g0 = acc[ai][0][m][n], v0 = acc[ai][1][m][n];
;                     f32x4 gp = (f32x4){0.f, 0.f, 0.f, 0.f}, vp = gp;
;                     if (m > 0) { gp = acc[ai][0][m > 0 ? m - 1 : 0][n]; vp = acc[ai][1][m > 0 ? m - 1 : 0][n]; }
;                     f32x4 f;
; #pragma unroll
;                     for (int j = 0; j < 4; ++j) {
;                         const float g1 = dpp_shr1(dpp_ror1(gp[j]), g0[j]), g2 = dpp_shr2(dpp_ror2(gp[j]), g0[j]);
;                         const float v1 = dpp_shr1(dpp_ror1(vp[j]), v0[j]), v2 = dpp_shr2(dpp_ror2(vp[j]), v0[j]);
;                         const float cg_ = bg[j] + g2 * wg0[j] + g1 * wg1[j] + g0[j] * wg2[j];
;                         const float cv_ = bv[j] + v2 * wv0[j] + v1 * wv1[j] + v0[j] * wv2[j];
;                         f[j] = gelu_tanh(cg_) * cv_; }
;                     u32x2 w; w.x = pk2(f[0], f[1]); w.y = pk2(f[2], f[3]);
;                     if (n == 0) res0[ai * 4 + m] = w;
;                     else if (m > 0 || fr >= 2) { u32x4 w4; w4.x = res0[ai * 4 + m].x; w4.y = res0[ai * 4 + m].y; w4.z = w.x; w4.w = w.y; *(u32x4*)(F + (size_t)row * DFF + j0) = w4; }
;                     if (n == 1 && ((m == 0 && fr < 2) || (m == 3 && fr >= 14))) { const int slot = m == 0 ? fr : fr - 12;
;                         const f32x4 ga = acc[ai][0][m][0], va = acc[ai][1][m][0];
;                         bf16_t* bp = UPB + ((size_t)(row >> 6) * 4 + slot) * (2 * DFF) + col0;
;                         u32x4 wg_, wv_; wg_.x = pk2(ga[0], ga[1]); wg_.y = pk2(ga[2], ga[3]); wg_.z = pk2(g0[0], g0[1]); wg_.w = pk2(g0[2], g0[3]);
;                         wv_.x = pk2(va[0], va[1]); wv_.y = pk2(va[2], va[3]); wv_.z = pk2(v0[0], v0[1]); wv_.w = pk2(v0[2], v0[3]);
;                         *(u32x4*)bp = wg_; *(u32x4*)(bp + HALF) = wv_; } }
	v_fmac_f32_dpp v139, v27, v205 row_shl:15 row_mask:0xf bank_mask:0xf
	v_fmac_f32_dpp v132, v28, v182 row_shr:2 row_mask:0xf bank_mask:0xf
	v_fmac_f32_dpp v133, v29, v183 row_shr:2 row_mask:0xf bank_mask:0xf
	v_fmac_f32_dpp v134, v30, v184 row_shr:2 row_mask:0xf bank_mask:0xf
	v_fmac_f32_dpp v135, v31, v185 row_shr:2 row_mask:0xf bank_mask:0xf
	v_fmac_f32_dpp v136, v8, v198 row_shr:2 row_mask:0xf bank_mask:0xf
	v_fmac_f32_dpp v137, v9, v199 row_shr:2 row_mask:0xf bank_mask:0xf
	v_fmac_f32_dpp v138, v10, v200 row_shr:2 row_mask:0xf bank_mask:0xf
	v_fmac_f32_dpp v139, v11, v201 row_shr:2 row_mask:0xf bank_mask:0xf
	v_fmac_f32_dpp v132, v44, v182 row_shl:14 row_mask:0xf bank_mask:0xf
	v_fmac_f32_dpp v133, v45, v183 row_shl:14 row_mask:0xf bank_mask:0xf
	v_fmac_f32_dpp v134, v46, v184 row_shl:14 row_mask:0xf bank_mask:0xf
	v_fmac_f32_dpp v135, v47, v185 row_shl:14 row_mask:0xf bank_mask:0xf
	v_fmac_f32_dpp v136, v24, v198 row_shl:14 row_mask:0xf bank_mask:0xf
	v_fmac_f32_dpp v137, v25, v199 row_shl:14 row_mask:0xf bank_mask:0xf
	v_fmac_f32_dpp v138, v26, v200 row_shl:14 row_mask:0xf bank_mask:0xf
	v_fmac_f32_dpp v139, v27, v201 row_shl:14 row_mask:0xf bank_mask:0xf
	v_pk_mul_f32 v[140:141], v[132:133], v[132:133]
	v_pk_mul_f32 v[142:143], v[134:135], v[134:135]
	v_pk_fma_f32 v[140:141], v[140:141], s[98:99], v[244:245]
	v_pk_fma_f32 v[142:143], v[142:143], s[98:99], v[244:245]
	v_pk_mul_f32 v[140:141], v[132:133], v[140:141]
	v_pk_mul_f32 v[142:143], v[134:135], v[142:143]
	v_exp_f32_e32 v140, v140
	v_exp_f32_e32 v141, v141
	v_exp_f32_e32 v142, v142
	v_exp_f32_e32 v143, v143
	v_pk_add_f32 v[140:141], v[140:141], s[100:101]
	v_pk_add_f32 v[142:143], v[142:143], s[100:101]
	v_rcp_f32_e32 v140, v140
	v_rcp_f32_e32 v141, v141
	v_rcp_f32_e32 v142, v142
	v_rcp_f32_e32 v143, v143
	v_pk_mul_f32 v[140:141], v[132:133], v[140:141]
	v_pk_mul_f32 v[142:143], v[134:135], v[142:143]
	v_pk_mul_f32 v[140:141], v[140:141], v[136:137]
	v_pk_mul_f32 v[142:143], v[142:143], v[138:139]
	v_cvt_pk_bf16_f32 v130, v140, v141
	v_cvt_pk_bf16_f32 v131, v142, v143
	v_add_u32_e32 v144, 0xa0, v248
	v_mad_u64_u32 v[144:145], vcc, v144, s4, v[242:243]
	global_store_dwordx4 v[144:145], v[128:131], off nt
	v_pk_fma_f32 v[132:133], v[20:21], v[158:159], v[146:147]
	v_pk_fma_f32 v[136:137], v[4:5], v[174:175], v[162:163]
	v_pk_fma_f32 v[134:135], v[22:23], v[160:161], v[148:149]
	v_pk_fma_f32 v[138:139], v[6:7], v[176:177], v[164:165]
	v_fmac_f32_dpp v132, v20, v154 row_shr:1 row_mask:0xf bank_mask:0xf
	v_fmac_f32_dpp v133, v21, v155 row_shr:1 row_mask:0xf bank_mask:0xf
	v_fmac_f32_dpp v134, v22, v156 row_shr:1 row_mask:0xf bank_mask:0xf
	v_fmac_f32_dpp v135, v23, v157 row_shr:1 row_mask:0xf bank_mask:0xf
	v_fmac_f32_dpp v136, v4, v170 row_shr:1 row_mask:0xf bank_mask:0xf
	v_fmac_f32_dpp v137, v5, v171 row_shr:1 row_mask:0xf bank_mask:0xf
	v_fmac_f32_dpp v138, v6, v172 row_shr:1 row_mask:0xf bank_mask:0xf
	v_fmac_f32_dpp v139, v7, v173 row_shr:1 row_mask:0xf bank_mask:0xf
	v_fmac_f32_dpp v132, v36, v154 row_shl:15 row_mask:0xf bank_mask:0xf
	v_fmac_f32_dpp v133, v37, v155 row_shl:15 row_mask:0xf bank_mask:0xf
	v_fmac_f32_dpp v134, v38, v156 row_shl:15 row_mask:0xf bank_mask:0xf
	v_fmac_f32_dpp v135, v39, v157 row_shl:15 row_mask:0xf bank_mask:0xf
	v_fmac_f32_dpp v136, v16, v170 row_shl:15 row_mask:0xf bank_mask:0xf
	v_fmac_f32_dpp v137, v17, v171 row_shl:15 row_mask:0xf bank_mask:0xf
	v_fmac_f32_dpp v138, v18, v172 row_shl:15 row_mask:0xf bank_mask:0xf
	v_fmac_f32_dpp v139, v19, v173 row_shl:15 row_mask:0xf bank_mask:0xf
	v_fmac_f32_dpp v132, v20, v150 row_shr:2 row_mask:0xf bank_mask:0xf
	v_fmac_f32_dpp v133, v21, v151 row_shr:2 row_mask:0xf bank_mask:0xf
	v_fmac_f32_dpp v134, v22, v152 row_shr:2 row_mask:0xf bank_mask:0xf
	v_fmac_f32_dpp v135, v23, v153 row_shr:2 row_mask:0xf bank_mask:0xf
	v_fmac_f32_dpp v136, v4, v166 row_shr:2 row_mask:0xf bank_mask:0xf
	v_fmac_f32_dpp v137, v5, v167 row_shr:2 row_mask:0xf bank_mask:0xf
	v_fmac_f32_dpp v138, v6, v168 row_shr:2 row_mask:0xf bank_mask:0xf
	v_fmac_f32_dpp v139, v7, v169 row_shr:2 row_mask:0xf bank_mask:0xf
	v_fmac_f32_dpp v132, v36, v150 row_shl:14 row_mask:0xf bank_mask:0xf
	v_fmac_f32_dpp v133, v37, v151 row_shl:14 row_mask:0xf bank_mask:0xf
	v_fmac_f32_dpp v134, v38, v152 row_shl:14 row_mask:0xf bank_mask:0xf
	v_fmac_f32_dpp v135, v39, v153 row_shl:14 row_mask:0xf bank_mask:0xf
	v_fmac_f32_dpp v136, v16, v166 row_shl:14 row_mask:0xf bank_mask:0xf
	v_fmac_f32_dpp v137, v17, v167 row_shl:14 row_mask:0xf bank_mask:0xf
	v_fmac_f32_dpp v138, v18, v168 row_shl:14 row_mask:0xf bank_mask:0xf
	v_fmac_f32_dpp v139, v19, v169 row_shl:14 row_mask:0xf bank_mask:0xf
	v_pk_mul_f32 v[140:141], v[132:133], v[132:133]
	v_pk_mul_f32 v[142:143], v[134:135], v[134:135]
	v_pk_fma_f32 v[140:141], v[140:141], s[98:99], v[244:245]
; __device__ __forceinline__ unsigned pk2(float lo, float hi) { unsigned r; asm("v_cvt_pk_bf16_f32 %0, %1, %2" : "=v"(r) : "v"(lo), "v"(hi)); return r; }
;     __device__ __forceinline__ void operator()(const f32x4 (&acc)[2][2][4][2], const Unit& u, int wr, int wc, int fr, int fq) const {
;     ...
; #pragma unroll
;             for (int ai = 0; ai < 2; ++ai)
; #pragma unroll
;                 for (int m = 0; m < 4; ++m) { const int row = row0 + ai * HALF + m * 16;
;                     const f32x4 g0 = acc[ai][0][m][n], v0 = acc[ai][1][m][n];
;                     f32x4 gp = (f32x4){0.f, 0.f, 0.f, 0.f}, vp = gp;
;                     if (m > 0) { gp = acc[ai][0][m > 0 ? m - 1 : 0][n]; vp = acc[ai][1][m > 0 ? m - 1 : 0][n]; }
;                     f32x4 f;
; #pragma unroll
;                     for (int j = 0; j < 4; ++j) {
;                         const float g1 = dpp_shr1(dpp_ror1(gp[j]), g0[j]), g2 = dpp_shr2(dpp_ror2(gp[j]), g0[j]);
;                         const float v1 = dpp_shr1(dpp_ror1(vp[j]), v0[j]), v2 = dpp_shr2(dpp_ror2(vp[j]), v0[j]);
;                         const float cg_ = bg[j] + g2 * wg0[j] + g1 * wg1[j] + g0[j] * wg2[j];
;                         const float cv_ = bv[j] + v2 * wv0[j] + v1 * wv1[j] + v0[j] * wv2[j];
;                         f[j] = gelu_tanh(cg_) * cv_; }
;                     u32x2 w; w.x = pk2(f[0], f[1]); w.y = pk2(f[2], f[3]);
;                     if (n == 0) res0[ai * 4 + m] = w;
;                     else if (m > 0 || fr >= 2) { u32x4 w4; w4.x = res0[ai * 4 + m].x; w4.y = res0[ai * 4 + m].y; w4.z = w.x; w4.w = w.y; *(u32x4*)(F + (size_t)row * DFF + j0) = w4; }
;                     if (n == 1 && ((m == 0 && fr < 2) || (m == 3 && fr >= 14))) { const int slot = m == 0 ? fr : fr - 12;
;                         const f32x4 ga = acc[ai][0][m][0], va = acc[ai][1][m][0];
;                         bf16_t* bp = UPB + ((size_t)(row >> 6) * 4 + slot) * (2 * DFF) + col0;
;                         u32x4 wg_, wv_; wg_.x = pk2(ga[0], ga[1]); wg_.y = pk2(ga[2], ga[3]); wg_.z = pk2(g0[0], g0[1]); wg_.w = pk2(g0[2], g0[3]);
;                         wv_.x = pk2(va[0], va[1]); wv_.y = pk2(va[2], va[3]); wv_.z = pk2(v0[0], v0[1]); wv_.w = pk2(v0[2], v0[3]);
;                         *(u32x4*)bp = wg_; *(u32x4*)(bp + HALF) = wv_; } }
	v_pk_fma_f32 v[142:143], v[142:143], s[98:99], v[244:245]
	v_pk_mul_f32 v[140:141], v[132:133], v[140:141]
	v_pk_mul_f32 v[142:143], v[134:135], v[142:143]
	v_exp_f32_e32 v140, v140
	v_exp_f32_e32 v141, v141
	v_exp_f32_e32 v142, v142
	v_exp_f32_e32 v143, v143
	v_pk_add_f32 v[140:141], v[140:141], s[100:101]
	v_pk_add_f32 v[142:143], v[142:143], s[100:101]
	v_rcp_f32_e32 v140, v140
	v_rcp_f32_e32 v141, v141
	v_rcp_f32_e32 v142, v142
	v_rcp_f32_e32 v143, v143
	v_pk_mul_f32 v[140:141], v[132:133], v[140:141]
	v_pk_mul_f32 v[142:143], v[134:135], v[142:143]
	v_pk_mul_f32 v[140:141], v[140:141], v[136:137]
	v_pk_mul_f32 v[142:143], v[142:143], v[138:139]
	v_cvt_pk_bf16_f32 v250, v140, v141
	v_cvt_pk_bf16_f32 v251, v142, v143
	v_pk_fma_f32 v[132:133], v[12:13], v[190:191], v[178:179]
	v_pk_fma_f32 v[136:137], v[0:1], v[206:207], v[194:195]
	v_pk_fma_f32 v[134:135], v[14:15], v[192:193], v[180:181]
	v_pk_fma_f32 v[138:139], v[2:3], v[208:209], v[196:197]
	v_fmac_f32_dpp v132, v12, v186 row_shr:1 row_mask:0xf bank_mask:0xf
	v_fmac_f32_dpp v133, v13, v187 row_shr:1 row_mask:0xf bank_mask:0xf
	v_fmac_f32_dpp v134, v14, v188 row_shr:1 row_mask:0xf bank_mask:0xf
	v_fmac_f32_dpp v135, v15, v189 row_shr:1 row_mask:0xf bank_mask:0xf
	v_fmac_f32_dpp v136, v0, v202 row_shr:1 row_mask:0xf bank_mask:0xf
	v_fmac_f32_dpp v137, v1, v203 row_shr:1 row_mask:0xf bank_mask:0xf
	v_fmac_f32_dpp v138, v2, v204 row_shr:1 row_mask:0xf bank_mask:0xf
	v_fmac_f32_dpp v139, v3, v205 row_shr:1 row_mask:0xf bank_mask:0xf
	v_fmac_f32_dpp v132, v28, v186 row_shl:15 row_mask:0xf bank_mask:0xf
	v_fmac_f32_dpp v133, v29, v187 row_shl:15 row_mask:0xf bank_mask:0xf
	v_fmac_f32_dpp v134, v30, v188 row_shl:15 row_mask:0xf bank_mask:0xf
	v_fmac_f32_dpp v135, v31, v189 row_shl:15 row_mask:0xf bank_mask:0xf
	v_fmac_f32_dpp v136, v8, v202 row_shl:15 row_mask:0xf bank_mask:0xf
	v_fmac_f32_dpp v137, v9, v203 row_shl:15 row_mask:0xf bank_mask:0xf
	v_fmac_f32_dpp v138, v10, v204 row_shl:15 row_mask:0xf bank_mask:0xf
	v_fmac_f32_dpp v139, v11, v205 row_shl:15 row_mask:0xf bank_mask:0xf
	v_fmac_f32_dpp v132, v12, v182 row_shr:2 row_mask:0xf bank_mask:0xf
	v_fmac_f32_dpp v133, v13, v183 row_shr:2 row_mask:0xf bank_mask:0xf
	v_fmac_f32_dpp v134, v14, v184 row_shr:2 row_mask:0xf bank_mask:0xf
	v_fmac_f32_dpp v135, v15, v185 row_shr:2 row_mask:0xf bank_mask:0xf
	v_fmac_f32_dpp v136, v0, v198 row_shr:2 row_mask:0xf bank_mask:0xf
	v_fmac_f32_dpp v137, v1, v199 row_shr:2 row_mask:0xf bank_mask:0xf
	v_fmac_f32_dpp v138, v2, v200 row_shr:2 row_mask:0xf bank_mask:0xf
	v_fmac_f32_dpp v139, v3, v201 row_shr:2 row_mask:0xf bank_mask:0xf
	v_fmac_f32_dpp v132, v28, v182 row_shl:14 row_mask:0xf bank_mask:0xf
	v_fmac_f32_dpp v133, v29, v183 row_shl:14 row_mask:0xf bank_mask:0xf
	v_fmac_f32_dpp v134, v30, v184 row_shl:14 row_mask:0xf bank_mask:0xf
	v_fmac_f32_dpp v135, v31, v185 row_shl:14 row_mask:0xf bank_mask:0xf
	v_fmac_f32_dpp v136, v8, v198 row_shl:14 row_mask:0xf bank_mask:0xf
	v_fmac_f32_dpp v137, v9, v199 row_shl:14 row_mask:0xf bank_mask:0xf
	v_fmac_f32_dpp v138, v10, v200 row_shl:14 row_mask:0xf bank_mask:0xf
	v_fmac_f32_dpp v139, v11, v201 row_shl:14 row_mask:0xf bank_mask:0xf
	v_pk_mul_f32 v[140:141], v[132:133], v[132:133]
	v_pk_mul_f32 v[142:143], v[134:135], v[134:135]
	v_pk_fma_f32 v[140:141], v[140:141], s[98:99], v[244:245]
	v_pk_fma_f32 v[142:143], v[142:143], s[98:99], v[244:245]
	v_pk_mul_f32 v[140:141], v[132:133], v[140:141]
	v_pk_mul_f32 v[142:143], v[134:135], v[142:143]
	v_exp_f32_e32 v140, v140
	v_exp_f32_e32 v141, v141
	v_exp_f32_e32 v142, v142
	v_exp_f32_e32 v143, v143
	v_pk_add_f32 v[140:141], v[140:141], s[100:101]
	v_pk_add_f32 v[142:143], v[142:143], s[100:101]
	v_rcp_f32_e32 v140, v140
	v_rcp_f32_e32 v141, v141
	v_rcp_f32_e32 v142, v142
	v_rcp_f32_e32 v143, v143
	v_pk_mul_f32 v[140:141], v[132:133], v[140:141]
	v_pk_mul_f32 v[142:143], v[134:135], v[142:143]
	v_pk_mul_f32 v[140:141], v[140:141], v[136:137]
	v_pk_mul_f32 v[142:143], v[142:143], v[138:139]
	v_cvt_pk_bf16_f32 v252, v140, v141
	v_cvt_pk_bf16_f32 v253, v142, v143
	v_add_u32_e32 v144, 0xb0, v248
	v_mad_u64_u32 v[144:145], vcc, v144, s4, v[242:243]
	global_store_dwordx4 v[144:145], v[250:253], off nt
	s_mov_b64 s[0:1], 0
	s_and_saveexec_b64 s[42:43], s[12:13]
	s_xor_b64 s[52:53], exec, s[42:43]
	s_cbranch_execz .LBB0_1214
	v_add_u32_e32 v144, s73, v234
	v_mov_b64_e32 v[132:133], s[80:81]
	v_mad_u64_u32 v[132:133], vcc, v144, s83, v[132:133]
	v_lshl_add_u64 v[132:133], v[240:241], 1, v[132:133]
	s_mov_b64 s[72:73], exec
	v_cvt_pk_bf16_f32 v134, v20, v21
	v_cvt_pk_bf16_f32 v135, v22, v23
	v_cvt_pk_bf16_f32 v136, v12, v13
	v_cvt_pk_bf16_f32 v137, v14, v15
	v_cvt_pk_bf16_f32 v128, v4, v5
	v_cvt_pk_bf16_f32 v129, v6, v7
	v_cvt_pk_bf16_f32 v130, v0, v1
	v_cvt_pk_bf16_f32 v131, v2, v3
	global_store_dwordx4 v[132:133], v[134:137], off

; #define PG8_STAGE(bufoff, gbase, voff) do { _Pragma("unroll") for (int _i = 0; _i < 2; ++_i) \
;         __builtin_amdgcn_global_load_lds((const unsigned*)((const char*)(gbase) + (voff)[_i]), (LAS unsigned*)(lds + (bufoff) + ldsw + _i * 8192), 16, 0, 0); } while (0)
; #define PG8_LDA(dst, b, h) do { _Pragma("unroll") for (int m = 0; m < 4; ++m) _Pragma("unroll") for (int k = 0; k < 2; ++k) dst[m][k] = *(const LAS bf16x8*)(lds + PG8_SA(b, h) + aoff + m * 2048 + k * 1024); } while (0)
; #define PG8_WAIT_V(n) asm volatile("s_waitcnt vmcnt(" #n ")" ::: "memory")
; #define PG8_WAIT_L(n) asm volatile("s_waitcnt lgkmcnt(" #n ")" ::: "memory")
; template <class Epi, class S_t>
; __device__ __forceinline__ void gemm_phase(LAS unsigned char* lds, int lda, int ldb, const S_t& S, const Epi& E) {
;     ...
;         for (int t = 0; t < nt; t += 2) {
;             const bool last = (t == nt - 2);
;             const char* a1 = cA + (size_t)(t + 1) * kstep;
;             const char* a2 = last ? nA : cA + (size_t)(t + 2) * kstep; const char* b2 = last ? nB : cB + (size_t)(t + 2) * kstep;
;             const char* a3 = a2 + kstep; const char* b3 = b2 + kstep;
;             PG8_LDB(B0, 0, 0); PG8_SCHED; PG8_LDA(At, 0, 0); PG8_STAGE(PG8_SA(1, 1), a1 + hstepA, voffA);
;             PG8_WAIT_L(8); PG8_BAR; PG8_WAIT_L(0); PG8_MMA(0, 0, At, B0); PG8_BAR; PG8_SCHED;
;             PG8_LDB(B1, 0, 1); PG8_STAGE(PG8_SB(0, 0), b2, voffB);
;             PG8_BAR; PG8_WAIT_L(0); PG8_MMA(0, 1, At, B1); PG8_BAR;
;             PG8_LDA(At, 0, 1); PG8_STAGE(PG8_SA(0, 0), a2, voffA);
;             PG8_BAR; PG8_WAIT_L(0); PG8_MMA(1, 0, At, B0); PG8_BAR; PG8_SCHED;
;             PG8_STAGE(PG8_SB(0, 1), b2 + hstepB, voffB);
;             PG8_WAIT_V(6); PG8_BAR; PG8_MMA(1, 1, At, B1); PG8_BAR;
;             PG8_LDB(B0, 1, 0); PG8_SCHED; PG8_LDA(At, 1, 0); PG8_STAGE(PG8_SA(0, 1), a2 + hstepA, voffA);
;             PG8_WAIT_L(8); PG8_BAR; PG8_WAIT_L(0); PG8_MMA(0, 0, At, B0); PG8_BAR; PG8_SCHED;
;             PG8_LDB(B1, 1, 1); PG8_STAGE(PG8_SB(1, 0), b3, voffB);
;             PG8_BAR; PG8_WAIT_L(0); PG8_MMA(0, 1, At, B1); PG8_BAR;
;             PG8_LDA(At, 1, 1); PG8_STAGE(PG8_SA(1, 0), a3, voffA);
;             PG8_BAR; PG8_WAIT_L(0); PG8_MMA(1, 0, At, B0); PG8_BAR; PG8_SCHED;
;             PG8_STAGE(PG8_SB(1, 1), b3 + hstepB, voffB);
;             PG8_WAIT_V(6); PG8_BAR; PG8_MMA(1, 1, At, B1); PG8_BAR;
.Lprio_b1200:
	ds_read_b128 v[128:131], v223
	ds_read_b128 v[132:135], v223 offset:1024
	ds_read_b128 v[136:139], v223 offset:2048
	ds_read_b128 v[140:143], v223 offset:3072
	s_add_u32 s33, s74, 0xfff80080
	s_addc_u32 s43, s75, -1
	s_cmp_eq_u32 s5, 28
	s_cselect_b32 s79, s69, s43
	s_cselect_b32 s78, s68, s33
	s_cselect_b32 s77, s71, s1
	s_cselect_b32 s76, s70, s0
	s_add_i32 m0, s7, 0xc000
	ds_read_b128 v[144:147], v246
	ds_read_b128 v[148:151], v246 offset:1024
	ds_read_b128 v[152:155], v246 offset:2048
	ds_read_b128 v[156:159], v246 offset:3072
	ds_read_b128 v[160:163], v246 offset:4096
	ds_read_b128 v[164:167], v246 offset:5120
	ds_read_b128 v[168:171], v246 offset:6144
	ds_read_b128 v[172:175], v246 offset:7168
	global_load_lds_dwordx4 v236, s[74:75]
	s_add_i32 m0, s7, 0xe000
	s_nop 0
	global_load_lds_dwordx4 v238, s[74:75]
	s_waitcnt lgkmcnt(8)
	s_barrier
	s_waitcnt lgkmcnt(0)
	s_setprio 2
	s_waitcnt lgkmcnt(0)
	v_mfma_f32_16x16x32_bf16 v[124:127], v[128:131], v[144:147], v[124:127]
	v_mfma_f32_16x16x32_bf16 v[120:123], v[136:139], v[144:147], v[120:123]
	v_mfma_f32_16x16x32_bf16 v[116:119], v[128:131], v[152:155], v[116:119]
	v_mfma_f32_16x16x32_bf16 v[108:111], v[136:139], v[152:155], v[108:111]
	v_mfma_f32_16x16x32_bf16 v[100:103], v[128:131], v[160:163], v[100:103]
	v_mfma_f32_16x16x32_bf16 v[92:95], v[136:139], v[160:163], v[92:95]
	v_mfma_f32_16x16x32_bf16 v[84:87], v[128:131], v[168:171], v[84:87]
	v_mfma_f32_16x16x32_bf16 v[76:79], v[136:139], v[168:171], v[76:79]
	v_mfma_f32_16x16x32_bf16 v[124:127], v[132:135], v[148:151], v[124:127]
	v_mfma_f32_16x16x32_bf16 v[120:123], v[140:143], v[148:151], v[120:123]
	v_mfma_f32_16x16x32_bf16 v[116:119], v[132:135], v[156:159], v[116:119]
	v_mfma_f32_16x16x32_bf16 v[108:111], v[140:143], v[156:159], v[108:111]
	v_mfma_f32_16x16x32_bf16 v[100:103], v[132:135], v[164:167], v[100:103]
	v_mfma_f32_16x16x32_bf16 v[92:95], v[140:143], v[164:167], v[92:95]
	v_mfma_f32_16x16x32_bf16 v[84:87], v[132:135], v[172:175], v[84:87]
	v_mfma_f32_16x16x32_bf16 v[76:79], v[140:143], v[172:175], v[76:79]
	s_setprio 1
	s_barrier
	s_add_i32 s33, s88, s64
	s_add_u32 s98, s76, s38
	s_addc_u32 s99, s77, s39
	s_mov_b32 m0, s33
	ds_read_b128 v[176:179], v247
	ds_read_b128 v[180:183], v247 offset:1024
	ds_read_b128 v[184:187], v247 offset:2048
	ds_read_b128 v[188:191], v247 offset:3072
	global_load_lds_dwordx4 v228, s[76:77]
	s_add_i32 m0, s33, 0x2000
	s_nop 0
	global_load_lds_dwordx4 v224, s[76:77]
	s_barrier
	s_waitcnt lgkmcnt(0)
	s_setprio 2
	s_waitcnt lgkmcnt(0)
	v_mfma_f32_16x16x32_bf16 v[112:115], v[176:179], v[144:147], v[112:115]
	v_mfma_f32_16x16x32_bf16 v[104:107], v[184:187], v[144:147], v[104:107]
	v_mfma_f32_16x16x32_bf16 v[96:99], v[176:179], v[152:155], v[96:99]
	v_mfma_f32_16x16x32_bf16 v[88:91], v[184:187], v[152:155], v[88:91]
	v_mfma_f32_16x16x32_bf16 v[80:83], v[176:179], v[160:163], v[80:83]
	v_mfma_f32_16x16x32_bf16 v[72:75], v[184:187], v[160:163], v[72:75]
	v_mfma_f32_16x16x32_bf16 v[68:71], v[176:179], v[168:171], v[68:71]
	v_mfma_f32_16x16x32_bf16 v[64:67], v[184:187], v[168:171], v[64:67]
	v_mfma_f32_16x16x32_bf16 v[112:115], v[180:183], v[148:151], v[112:115]
	v_mfma_f32_16x16x32_bf16 v[104:107], v[188:191], v[148:151], v[104:107]
	v_mfma_f32_16x16x32_bf16 v[96:99], v[180:183], v[156:159], v[96:99]
	v_mfma_f32_16x16x32_bf16 v[88:91], v[188:191], v[156:159], v[88:91]
	v_mfma_f32_16x16x32_bf16 v[80:83], v[180:183], v[164:167], v[80:83]
	v_mfma_f32_16x16x32_bf16 v[72:75], v[188:191], v[164:167], v[72:75]
	v_mfma_f32_16x16x32_bf16 v[68:71], v[180:183], v[172:175], v[68:71]
	v_mfma_f32_16x16x32_bf16 v[64:67], v[188:191], v[172:175], v[64:67]
	s_setprio 1
	s_mov_b32 m0, s7
	s_add_u32 s100, s78, s38
	s_addc_u32 s101, s79, s39
	s_barrier
	ds_read_b128 v[144:147], v246 offset:16384
	ds_read_b128 v[148:151], v246 offset:17408
	ds_read_b128 v[152:155], v246 offset:18432
	ds_read_b128 v[156:159], v246 offset:19456
	ds_read_b128 v[160:163], v246 offset:20480
	ds_read_b128 v[164:167], v246 offset:21504
	ds_read_b128 v[168:171], v246 offset:22528
	ds_read_b128 v[172:175], v246 offset:23552
	global_load_lds_dwordx4 v230, s[78:79]
	s_mov_b32 m0, s35
	s_nop 0
	global_load_lds_dwordx4 v226, s[78:79]
	s_barrier
	s_waitcnt lgkmcnt(0)
	s_setprio 2
	s_waitcnt lgkmcnt(0)
	v_mfma_f32_16x16x32_bf16 v[60:63], v[128:131], v[144:147], v[60:63]
	v_mfma_f32_16x16x32_bf16 v[56:59], v[136:139], v[144:147], v[56:59]
	v_mfma_f32_16x16x32_bf16 v[52:55], v[128:131], v[152:155], v[52:55]
	v_mfma_f32_16x16x32_bf16 v[44:47], v[136:139], v[152:155], v[44:47]
	v_mfma_f32_16x16x32_bf16 v[36:39], v[128:131], v[160:163], v[36:39]
	v_mfma_f32_16x16x32_bf16 v[28:31], v[136:139], v[160:163], v[28:31]
	v_mfma_f32_16x16x32_bf16 v[20:23], v[128:131], v[168:171], v[20:23]
	v_mfma_f32_16x16x32_bf16 v[12:15], v[136:139], v[168:171], v[12:15]
	v_mfma_f32_16x16x32_bf16 v[60:63], v[132:135], v[148:151], v[60:63]
	v_mfma_f32_16x16x32_bf16 v[56:59], v[140:143], v[148:151], v[56:59]
	v_mfma_f32_16x16x32_bf16 v[52:55], v[132:135], v[156:159], v[52:55]
	v_mfma_f32_16x16x32_bf16 v[44:47], v[140:143], v[156:159], v[44:47]
	v_mfma_f32_16x16x32_bf16 v[36:39], v[132:135], v[164:167], v[36:39]
	v_mfma_f32_16x16x32_bf16 v[28:31], v[140:143], v[164:167], v[28:31]
	v_mfma_f32_16x16x32_bf16 v[20:23], v[132:135], v[172:175], v[20:23]
	v_mfma_f32_16x16x32_bf16 v[12:15], v[140:143], v[172:175], v[12:15]
	s_setprio 1
	s_barrier
	s_add_u32 s52, s76, 0x80000
	s_addc_u32 s53, s77, 0
	s_add_i32 s33, s89, s64
	s_mov_b32 m0, s33
	s_nop 0
	global_load_lds_dwordx4 v228, s[52:53]
	s_add_i32 m0, s33, 0x2000
	s_nop 0
	global_load_lds_dwordx4 v224, s[52:53]
	s_waitcnt vmcnt(6)
	s_barrier
; #define PG8_STAGE(bufoff, gbase, voff) do { _Pragma("unroll") for (int _i = 0; _i < 2; ++_i) \
;         __builtin_amdgcn_global_load_lds((const unsigned*)((const char*)(gbase) + (voff)[_i]), (LAS unsigned*)(lds + (bufoff) + ldsw + _i * 8192), 16, 0, 0); } while (0)
; #define PG8_LDA(dst, b, h) do { _Pragma("unroll") for (int m = 0; m < 4; ++m) _Pragma("unroll") for (int k = 0; k < 2; ++k) dst[m][k] = *(const LAS bf16x8*)(lds + PG8_SA(b, h) + aoff + m * 2048 + k * 1024); } while (0)
; #define PG8_WAIT_V(n) asm volatile("s_waitcnt vmcnt(" #n ")" ::: "memory")
; #define PG8_WAIT_L(n) asm volatile("s_waitcnt lgkmcnt(" #n ")" ::: "memory")
; template <class Epi, class S_t>
; __device__ __forceinline__ void gemm_phase(LAS unsigned char* lds, int lda, int ldb, const S_t& S, const Epi& E) {
;     ...
;         for (int t = 0; t < nt; t += 2) {
;             const bool last = (t == nt - 2);
;             const char* a1 = cA + (size_t)(t + 1) * kstep;
;             const char* a2 = last ? nA : cA + (size_t)(t + 2) * kstep; const char* b2 = last ? nB : cB + (size_t)(t + 2) * kstep;
;             const char* a3 = a2 + kstep; const char* b3 = b2 + kstep;
;             PG8_LDB(B0, 0, 0); PG8_SCHED; PG8_LDA(At, 0, 0); PG8_STAGE(PG8_SA(1, 1), a1 + hstepA, voffA);
;             PG8_WAIT_L(8); PG8_BAR; PG8_WAIT_L(0); PG8_MMA(0, 0, At, B0); PG8_BAR; PG8_SCHED;
;             PG8_LDB(B1, 0, 1); PG8_STAGE(PG8_SB(0, 0), b2, voffB);
;             PG8_BAR; PG8_WAIT_L(0); PG8_MMA(0, 1, At, B1); PG8_BAR;
;             PG8_LDA(At, 0, 1); PG8_STAGE(PG8_SA(0, 0), a2, voffA);
;             PG8_BAR; PG8_WAIT_L(0); PG8_MMA(1, 0, At, B0); PG8_BAR; PG8_SCHED;
;             PG8_STAGE(PG8_SB(0, 1), b2 + hstepB, voffB);
;             PG8_WAIT_V(6); PG8_BAR; PG8_MMA(1, 1, At, B1); PG8_BAR;
;             PG8_LDB(B0, 1, 0); PG8_SCHED; PG8_LDA(At, 1, 0); PG8_STAGE(PG8_SA(0, 1), a2 + hstepA, voffA);
;             PG8_WAIT_L(8); PG8_BAR; PG8_WAIT_L(0); PG8_MMA(0, 0, At, B0); PG8_BAR; PG8_SCHED;
;             PG8_LDB(B1, 1, 1); PG8_STAGE(PG8_SB(1, 0), b3, voffB);
;             PG8_BAR; PG8_WAIT_L(0); PG8_MMA(0, 1, At, B1); PG8_BAR;
;             PG8_LDA(At, 1, 1); PG8_STAGE(PG8_SA(1, 0), a3, voffA);
;             PG8_BAR; PG8_WAIT_L(0); PG8_MMA(1, 0, At, B0); PG8_BAR; PG8_SCHED;
;             PG8_STAGE(PG8_SB(1, 1), b3 + hstepB, voffB);
;             PG8_WAIT_V(6); PG8_BAR; PG8_MMA(1, 1, At, B1); PG8_BAR;
	s_setprio 2
	v_mfma_f32_16x16x32_bf16 v[48:51], v[176:179], v[144:147], v[48:51]
	v_mfma_f32_16x16x32_bf16 v[40:43], v[184:187], v[144:147], v[40:43]
	v_mfma_f32_16x16x32_bf16 v[32:35], v[176:179], v[152:155], v[32:35]
	v_mfma_f32_16x16x32_bf16 v[24:27], v[184:187], v[152:155], v[24:27]
	v_mfma_f32_16x16x32_bf16 v[16:19], v[176:179], v[160:163], v[16:19]
	v_mfma_f32_16x16x32_bf16 v[8:11], v[184:187], v[160:163], v[8:11]
	v_mfma_f32_16x16x32_bf16 v[4:7], v[176:179], v[168:171], v[4:7]
	v_mfma_f32_16x16x32_bf16 v[0:3], v[184:187], v[168:171], v[0:3]
	v_mfma_f32_16x16x32_bf16 v[48:51], v[180:183], v[148:151], v[48:51]
	v_mfma_f32_16x16x32_bf16 v[40:43], v[188:191], v[148:151], v[40:43]
	v_mfma_f32_16x16x32_bf16 v[32:35], v[180:183], v[156:159], v[32:35]
	v_mfma_f32_16x16x32_bf16 v[24:27], v[188:191], v[156:159], v[24:27]
	v_mfma_f32_16x16x32_bf16 v[16:19], v[180:183], v[164:167], v[16:19]
	v_mfma_f32_16x16x32_bf16 v[8:11], v[188:191], v[164:167], v[8:11]
	v_mfma_f32_16x16x32_bf16 v[4:7], v[180:183], v[172:175], v[4:7]
	v_mfma_f32_16x16x32_bf16 v[0:3], v[188:191], v[172:175], v[0:3]
	s_setprio 1
	v_add_u32_e32 v140, s90, v215
	s_barrier
	ds_read_b128 v[128:131], v140
	ds_read_b128 v[132:135], v140 offset:1024
	ds_read_b128 v[136:139], v140 offset:2048
	ds_read_b128 v[140:143], v140 offset:3072
	s_add_u32 s52, s78, 0x80000
	s_addc_u32 s53, s79, 0
	s_mov_b32 m0, s92
	ds_read_b128 v[144:147], v246 offset:32768
	ds_read_b128 v[148:151], v246 offset:33792
	ds_read_b128 v[152:155], v246 offset:34816
	ds_read_b128 v[156:159], v246 offset:35840
	ds_read_b128 v[160:163], v246 offset:36864
	ds_read_b128 v[164:167], v246 offset:37888
	ds_read_b128 v[168:171], v246 offset:38912
	ds_read_b128 v[172:175], v246 offset:39936
	global_load_lds_dwordx4 v230, s[52:53]
	s_mov_b32 m0, s50
	s_nop 0
	global_load_lds_dwordx4 v226, s[52:53]
	s_waitcnt lgkmcnt(8)
	s_barrier
	s_waitcnt lgkmcnt(0)
	s_setprio 2
	s_waitcnt lgkmcnt(0)
	v_mfma_f32_16x16x32_bf16 v[124:127], v[128:131], v[144:147], v[124:127]
	v_mfma_f32_16x16x32_bf16 v[120:123], v[136:139], v[144:147], v[120:123]
	v_mfma_f32_16x16x32_bf16 v[116:119], v[128:131], v[152:155], v[116:119]
	v_mfma_f32_16x16x32_bf16 v[108:111], v[136:139], v[152:155], v[108:111]
	v_mfma_f32_16x16x32_bf16 v[100:103], v[128:131], v[160:163], v[100:103]
	v_mfma_f32_16x16x32_bf16 v[92:95], v[136:139], v[160:163], v[92:95]
	v_mfma_f32_16x16x32_bf16 v[84:87], v[128:131], v[168:171], v[84:87]
	v_mfma_f32_16x16x32_bf16 v[76:79], v[136:139], v[168:171], v[76:79]
	v_mfma_f32_16x16x32_bf16 v[124:127], v[132:135], v[148:151], v[124:127]
	v_mfma_f32_16x16x32_bf16 v[120:123], v[140:143], v[148:151], v[120:123]
	v_mfma_f32_16x16x32_bf16 v[116:119], v[132:135], v[156:159], v[116:119]
	v_mfma_f32_16x16x32_bf16 v[108:111], v[140:143], v[156:159], v[108:111]
	v_mfma_f32_16x16x32_bf16 v[100:103], v[132:135], v[164:167], v[100:103]
	v_mfma_f32_16x16x32_bf16 v[92:95], v[140:143], v[164:167], v[92:95]
	v_mfma_f32_16x16x32_bf16 v[84:87], v[132:135], v[172:175], v[84:87]
	v_mfma_f32_16x16x32_bf16 v[76:79], v[140:143], v[172:175], v[76:79]
	s_setprio 1
	s_barrier
	s_add_i32 s33, s90, s64
	v_add_u32_e32 v188, s91, v215
	s_mov_b32 m0, s33
	ds_read_b128 v[176:179], v188
	ds_read_b128 v[180:183], v188 offset:1024
	ds_read_b128 v[184:187], v188 offset:2048
	ds_read_b128 v[188:191], v188 offset:3072
	global_load_lds_dwordx4 v228, s[98:99]
	s_add_i32 m0, s33, 0x2000
	s_nop 0
	global_load_lds_dwordx4 v224, s[98:99]
	s_barrier
; #define PG8_STAGE(bufoff, gbase, voff) do { _Pragma("unroll") for (int _i = 0; _i < 2; ++_i) \
;         __builtin_amdgcn_global_load_lds((const unsigned*)((const char*)(gbase) + (voff)[_i]), (LAS unsigned*)(lds + (bufoff) + ldsw + _i * 8192), 16, 0, 0); } while (0)
; #define PG8_LDA(dst, b, h) do { _Pragma("unroll") for (int m = 0; m < 4; ++m) _Pragma("unroll") for (int k = 0; k < 2; ++k) dst[m][k] = *(const LAS bf16x8*)(lds + PG8_SA(b, h) + aoff + m * 2048 + k * 1024); } while (0)
; #define PG8_WAIT_V(n) asm volatile("s_waitcnt vmcnt(" #n ")" ::: "memory")
; #define PG8_WAIT_L(n) asm volatile("s_waitcnt lgkmcnt(" #n ")" ::: "memory")
; template <class Epi, class S_t>
; __device__ __forceinline__ void gemm_phase(LAS unsigned char* lds, int lda, int ldb, const S_t& S, const Epi& E) {
;     ...
;         for (int t = 0; t < nt; t += 2) {
;             const bool last = (t == nt - 2);
;             const char* a1 = cA + (size_t)(t + 1) * kstep;
;             const char* a2 = last ? nA : cA + (size_t)(t + 2) * kstep; const char* b2 = last ? nB : cB + (size_t)(t + 2) * kstep;
;             const char* a3 = a2 + kstep; const char* b3 = b2 + kstep;
;             PG8_LDB(B0, 0, 0); PG8_SCHED; PG8_LDA(At, 0, 0); PG8_STAGE(PG8_SA(1, 1), a1 + hstepA, voffA);
;             PG8_WAIT_L(8); PG8_BAR; PG8_WAIT_L(0); PG8_MMA(0, 0, At, B0); PG8_BAR; PG8_SCHED;
;             PG8_LDB(B1, 0, 1); PG8_STAGE(PG8_SB(0, 0), b2, voffB);
;             PG8_BAR; PG8_WAIT_L(0); PG8_MMA(0, 1, At, B1); PG8_BAR;
;             PG8_LDA(At, 0, 1); PG8_STAGE(PG8_SA(0, 0), a2, voffA);
;             PG8_BAR; PG8_WAIT_L(0); PG8_MMA(1, 0, At, B0); PG8_BAR; PG8_SCHED;
;             PG8_STAGE(PG8_SB(0, 1), b2 + hstepB, voffB);
;             PG8_WAIT_V(6); PG8_BAR; PG8_MMA(1, 1, At, B1); PG8_BAR;
;             PG8_LDB(B0, 1, 0); PG8_SCHED; PG8_LDA(At, 1, 0); PG8_STAGE(PG8_SA(0, 1), a2 + hstepA, voffA);
;             PG8_WAIT_L(8); PG8_BAR; PG8_WAIT_L(0); PG8_MMA(0, 0, At, B0); PG8_BAR; PG8_SCHED;
;             PG8_LDB(B1, 1, 1); PG8_STAGE(PG8_SB(1, 0), b3, voffB);
;             PG8_BAR; PG8_WAIT_L(0); PG8_MMA(0, 1, At, B1); PG8_BAR;
;             PG8_LDA(At, 1, 1); PG8_STAGE(PG8_SA(1, 0), a3, voffA);
;             PG8_BAR; PG8_WAIT_L(0); PG8_MMA(1, 0, At, B0); PG8_BAR; PG8_SCHED;
;             PG8_STAGE(PG8_SB(1, 1), b3 + hstepB, voffB);
;             PG8_WAIT_V(6); PG8_BAR; PG8_MMA(1, 1, At, B1); PG8_BAR;
	s_waitcnt lgkmcnt(0)
	s_setprio 2
	s_waitcnt lgkmcnt(0)
	v_mfma_f32_16x16x32_bf16 v[112:115], v[176:179], v[144:147], v[112:115]
	v_mfma_f32_16x16x32_bf16 v[104:107], v[184:187], v[144:147], v[104:107]
	v_mfma_f32_16x16x32_bf16 v[96:99], v[176:179], v[152:155], v[96:99]
	v_mfma_f32_16x16x32_bf16 v[88:91], v[184:187], v[152:155], v[88:91]
	v_mfma_f32_16x16x32_bf16 v[80:83], v[176:179], v[160:163], v[80:83]
	v_mfma_f32_16x16x32_bf16 v[72:75], v[184:187], v[160:163], v[72:75]
	v_mfma_f32_16x16x32_bf16 v[68:71], v[176:179], v[168:171], v[68:71]
	v_mfma_f32_16x16x32_bf16 v[64:67], v[184:187], v[168:171], v[64:67]
	v_mfma_f32_16x16x32_bf16 v[112:115], v[180:183], v[148:151], v[112:115]
	v_mfma_f32_16x16x32_bf16 v[104:107], v[188:191], v[148:151], v[104:107]
	v_mfma_f32_16x16x32_bf16 v[96:99], v[180:183], v[156:159], v[96:99]
	v_mfma_f32_16x16x32_bf16 v[88:91], v[188:191], v[156:159], v[88:91]
	v_mfma_f32_16x16x32_bf16 v[80:83], v[180:183], v[164:167], v[80:83]
	v_mfma_f32_16x16x32_bf16 v[72:75], v[188:191], v[164:167], v[72:75]
	v_mfma_f32_16x16x32_bf16 v[68:71], v[180:183], v[172:175], v[68:71]
	v_mfma_f32_16x16x32_bf16 v[64:67], v[188:191], v[172:175], v[64:67]
	s_setprio 1
	s_mov_b32 m0, s96
	s_barrier
	ds_read_b128 v[144:147], v246 offset:49152
	ds_read_b128 v[148:151], v246 offset:50176
	ds_read_b128 v[152:155], v246 offset:51200
	ds_read_b128 v[156:159], v246 offset:52224
	ds_read_b128 v[160:163], v246 offset:53248
	ds_read_b128 v[164:167], v246 offset:54272
	ds_read_b128 v[168:171], v246 offset:55296
	ds_read_b128 v[172:175], v246 offset:56320
	global_load_lds_dwordx4 v230, s[100:101]
	s_mov_b32 m0, s97
	s_nop 0
	global_load_lds_dwordx4 v226, s[100:101]
	s_barrier
	s_waitcnt lgkmcnt(0)
	s_setprio 2
	s_waitcnt lgkmcnt(0)
	v_mfma_f32_16x16x32_bf16 v[60:63], v[128:131], v[144:147], v[60:63]
	v_mfma_f32_16x16x32_bf16 v[56:59], v[136:139], v[144:147], v[56:59]
	v_mfma_f32_16x16x32_bf16 v[52:55], v[128:131], v[152:155], v[52:55]
	v_mfma_f32_16x16x32_bf16 v[44:47], v[136:139], v[152:155], v[44:47]
	v_mfma_f32_16x16x32_bf16 v[36:39], v[128:131], v[160:163], v[36:39]
	v_mfma_f32_16x16x32_bf16 v[28:31], v[136:139], v[160:163], v[28:31]
	v_mfma_f32_16x16x32_bf16 v[20:23], v[128:131], v[168:171], v[20:23]
	v_mfma_f32_16x16x32_bf16 v[12:15], v[136:139], v[168:171], v[12:15]
	v_mfma_f32_16x16x32_bf16 v[60:63], v[132:135], v[148:151], v[60:63]
	v_mfma_f32_16x16x32_bf16 v[56:59], v[140:143], v[148:151], v[56:59]
	v_mfma_f32_16x16x32_bf16 v[52:55], v[132:135], v[156:159], v[52:55]
	v_mfma_f32_16x16x32_bf16 v[44:47], v[140:143], v[156:159], v[44:47]
	v_mfma_f32_16x16x32_bf16 v[36:39], v[132:135], v[164:167], v[36:39]
	v_mfma_f32_16x16x32_bf16 v[28:31], v[140:143], v[164:167], v[28:31]
	v_mfma_f32_16x16x32_bf16 v[20:23], v[132:135], v[172:175], v[20:23]
	v_mfma_f32_16x16x32_bf16 v[12:15], v[140:143], v[172:175], v[12:15]
	s_setprio 1
	s_barrier
	s_add_u32 s52, s76, 0x80080
	s_addc_u32 s53, s77, 0
	s_add_i32 s33, s91, s64
	s_mov_b32 m0, s33
	s_nop 0
	global_load_lds_dwordx4 v228, s[52:53]
	s_add_i32 m0, s33, 0x2000
	s_nop 0
	global_load_lds_dwordx4 v224, s[52:53]
	s_waitcnt vmcnt(6)
	s_barrier
	s_setprio 2
	v_mfma_f32_16x16x32_bf16 v[48:51], v[176:179], v[144:147], v[48:51]
	v_mfma_f32_16x16x32_bf16 v[40:43], v[184:187], v[144:147], v[40:43]
	v_mfma_f32_16x16x32_bf16 v[32:35], v[176:179], v[152:155], v[32:35]
	v_mfma_f32_16x16x32_bf16 v[24:27], v[184:187], v[152:155], v[24:27]
	v_mfma_f32_16x16x32_bf16 v[16:19], v[176:179], v[160:163], v[16:19]
	v_mfma_f32_16x16x32_bf16 v[8:11], v[184:187], v[160:163], v[8:11]
	v_mfma_f32_16x16x32_bf16 v[4:7], v[176:179], v[168:171], v[4:7]
	v_mfma_f32_16x16x32_bf16 v[0:3], v[184:187], v[168:171], v[0:3]
	v_mfma_f32_16x16x32_bf16 v[48:51], v[180:183], v[148:151], v[48:51]
	v_mfma_f32_16x16x32_bf16 v[40:43], v[188:191], v[148:151], v[40:43]
	v_mfma_f32_16x16x32_bf16 v[32:35], v[180:183], v[156:159], v[32:35]
	v_mfma_f32_16x16x32_bf16 v[24:27], v[188:191], v[156:159], v[24:27]
	v_mfma_f32_16x16x32_bf16 v[16:19], v[180:183], v[164:167], v[16:19]
	v_mfma_f32_16x16x32_bf16 v[8:11], v[188:191], v[164:167], v[8:11]
	v_mfma_f32_16x16x32_bf16 v[4:7], v[180:183], v[172:175], v[4:7]
	v_mfma_f32_16x16x32_bf16 v[0:3], v[188:191], v[172:175], v[0:3]
	s_setprio 1
	s_add_i32 s5, s5, 2
	s_add_u32 s74, s74, 0x100
	s_addc_u32 s75, s75, 0
	s_add_u32 s0, s0, 0x100
	s_addc_u32 s1, s1, 0
	s_cmp_gt_u32 s5, 29
	s_barrier
	s_cbranch_scc0 .Lprio_b1200
	s_setprio 0
	s_branch .Lprio_x1200
